# GEMM main loops: A-fragment LDS address adds hoisted out of the loop (base +0x10000 once, buffer distance in ds_read offset)
# baseline (speedup 1.0000x reference)
.LBB0_23:
	v_readlane_b32 s46, v252, 62
	v_readlane_b32 s47, v252, 63
	v_mov_b32_e32 v131, v1
	v_readlane_b32 s12, v252, 58
	v_lshl_add_u64 v[10:11], s[46:47], 0, v[0:1]
	v_lshl_add_u64 v[12:13], s[46:47], 0, v[130:131]
	v_mov_b32_e32 v135, v1
	v_readlane_b32 s13, v252, 59
	s_add_i32 m0, s53, 0x18000
	v_lshl_add_u64 v[10:11], v[10:11], 0, s[94:95]
	v_lshl_add_u64 v[14:15], s[12:13], 0, v[134:135]
	v_mov_b32_e32 v133, v1
	s_waitcnt vmcnt(4)
	s_barrier
	global_load_lds_dwordx4 v[10:11], off
	v_lshl_add_u64 v[10:11], v[12:13], 0, s[94:95]
	s_add_i32 m0, s53, 0x1a000
	s_add_i32 s57, s53, 0x8000
	v_lshl_add_u64 v[16:17], s[12:13], 0, v[132:133]
	global_load_lds_dwordx4 v[10:11], off
	v_lshl_add_u64 v[10:11], v[14:15], 0, s[94:95]
	s_mov_b32 m0, s57
	s_add_i32 s58, s53, 0xa000
	v_readlane_b32 s38, v253, 0
	global_load_lds_dwordx4 v[10:11], off
	v_lshl_add_u64 v[10:11], v[16:17], 0, s[94:95]
	s_mov_b32 m0, s58
	v_readlane_b32 s39, v253, 1
	global_load_lds_dwordx4 v[10:11], off
	s_add_i32 m0, s53, 0x1c000
	v_lshl_add_u64 v[10:11], s[38:39], 0, v[0:1]
	global_load_lds_dwordx4 v[10:11], off
	v_lshl_add_u64 v[10:11], s[38:39], 0, v[130:131]
	s_add_i32 m0, s53, 0x1e000
	v_bfe_u32 v19, v166, 4, 2
	global_load_lds_dwordx4 v[10:11], off
	v_and_b32_e32 v18, 15, v166
	v_lshlrev_b32_e32 v20, 4, v19
	v_lshl_or_b32 v152, s1, 6, v18
	v_lshl_or_b32 v18, v18, 6, v20
	v_lshlrev_b32_e32 v20, 2, v166
	s_lshl_b32 s0, s0, 5
	s_lshl_b32 s1, s1, 13
	v_and_b32_e32 v20, 32, v20
	s_and_b32 s0, s0, 0x60
	s_movk_i32 s38, 0x2c00
	v_bitop3_b32 v21, v18, s1, v20 bitop3:0xde
	s_lshl_b32 s1, s0, 7
	v_lshrrev_b32_e32 v7, 1, v7
	v_mul_lo_u32 v10, v9, s38
	s_mov_b32 s39, 0x2c000
	v_bitop3_b32 v153, s1, v18, v20 bitop3:0xf6
	v_add_u32_e32 v153, 0x10000, v153
	v_lshl_or_b32 v154, v19, 2, s0
	v_mad_u64_u32 v[10:11], s[0:1], v7, s39, v[10:11]
	v_or_b32_e32 v6, v10, v6
	v_add_lshl_u32 v6, v6, v8, 1
	v_mov_b32_e32 v7, v1
	s_mov_b64 s[40:41], 0x2c0080
	v_lshl_add_u64 v[136:137], v[6:7], 0, s[40:41]
	v_lshrrev_b32_e32 v3, 1, v3
	v_mul_lo_u32 v6, v5, s38
	v_mad_u64_u32 v[6:7], s[0:1], v3, s39, v[6:7]
	s_waitcnt vmcnt(6)
	v_or_b32_e32 v2, v6, v2
	v_add_lshl_u32 v2, v2, v4, 1
	v_mov_b32_e32 v3, v1
	v_readlane_b32 s0, v250, 8
	v_lshl_add_u64 v[138:139], v[2:3], 0, s[40:41]
	s_mov_b32 s59, 0
	v_add_u32_e32 v155, 0, v21
	v_readlane_b32 s39, v252, 53
	v_readlane_b32 s66, v252, 51
	v_readlane_b32 s67, v252, 52
	v_readlane_b32 s65, v252, 54
	s_mov_b32 s38, s0
	s_mov_b64 s[0:1], s[12:13]
	s_barrier
	s_branch .LBB0_25

.LBB0_37:
	s_add_i32 s69, s48, 2
	s_add_u32 s46, s0, 0x100
	s_addc_u32 s47, s1, 0
	s_add_i32 s70, 0, 0x10000
	ds_read_b128 v[140:143], v153
	ds_read_b128 v[144:147], v153 offset:1024
	ds_read_b128 v[148:151], v153 offset:2048
	ds_read_b128 v[168:171], v153 offset:3072
	s_cmp_eq_u32 s12, s48
	s_cselect_b32 s48, s44, s13
	s_cselect_b32 s51, s43, s47
	s_cselect_b32 s50, s42, s46
	s_cselect_b32 s49, s45, s68
	v_lshl_add_u64 v[156:157], s[0:1], 0, v[136:137]
	s_add_i32 m0, s53, 0xc000
	ds_read_b128 v[172:175], v155
	ds_read_b128 v[176:179], v155 offset:1024
	ds_read_b128 v[180:183], v155 offset:2048
	ds_read_b128 v[184:187], v155 offset:3072
	ds_read_b128 v[188:191], v155 offset:4096
	ds_read_b128 v[192:195], v155 offset:5120
	ds_read_b128 v[196:199], v155 offset:6144
	ds_read_b128 v[224:227], v155 offset:7168
	global_load_lds_dwordx4 v[156:157], off
	v_lshl_add_u64 v[156:157], s[0:1], 0, v[138:139]
	s_add_i32 m0, s53, 0xe000
	s_nop 0
	global_load_lds_dwordx4 v[156:157], off
	s_waitcnt lgkmcnt(8)
	s_barrier
	s_waitcnt lgkmcnt(0)
	s_waitcnt lgkmcnt(0)
	v_mfma_f32_16x16x32_bf16 v[126:129], v[140:143], v[172:175], v[126:129]
	v_mfma_f32_16x16x32_bf16 v[122:125], v[148:151], v[172:175], v[122:125]
	v_mfma_f32_16x16x32_bf16 v[110:113], v[140:143], v[180:183], v[110:113]
	v_mfma_f32_16x16x32_bf16 v[106:109], v[148:151], v[180:183], v[106:109]
	v_mfma_f32_16x16x32_bf16 v[94:97], v[140:143], v[188:191], v[94:97]
	v_mfma_f32_16x16x32_bf16 v[90:93], v[148:151], v[188:191], v[90:93]
	v_mfma_f32_16x16x32_bf16 v[78:81], v[140:143], v[196:199], v[78:81]
	v_mfma_f32_16x16x32_bf16 v[74:77], v[148:151], v[196:199], v[74:77]
	v_mfma_f32_16x16x32_bf16 v[126:129], v[144:147], v[176:179], v[126:129]
	v_mfma_f32_16x16x32_bf16 v[122:125], v[168:171], v[176:179], v[122:125]
	v_mfma_f32_16x16x32_bf16 v[110:113], v[144:147], v[184:187], v[110:113]
	v_mfma_f32_16x16x32_bf16 v[106:109], v[168:171], v[184:187], v[106:109]
	v_mfma_f32_16x16x32_bf16 v[94:97], v[144:147], v[192:195], v[94:97]
	v_mfma_f32_16x16x32_bf16 v[90:93], v[168:171], v[192:195], v[90:93]
	v_mfma_f32_16x16x32_bf16 v[78:81], v[144:147], v[224:227], v[78:81]
	v_mfma_f32_16x16x32_bf16 v[74:77], v[168:171], v[224:227], v[74:77]
	s_barrier
	s_add_i32 s71, 0, 0x14000
	s_add_i32 s0, s70, s52
	ds_read_b128 v[228:231], v153 offset:16384
	ds_read_b128 v[232:235], v153 offset:17408
	ds_read_b128 v[236:239], v153 offset:18432
	ds_read_b128 v[240:243], v153 offset:19456
	s_add_u32 s76, s48, s94
	s_addc_u32 s77, s49, s95
	s_mov_b32 m0, s0
	s_nop 0
	global_load_lds_dwordx4 v0, s[48:49]
	s_add_i32 m0, s0, 0x2000
	s_nop 0
	global_load_lds_dwordx4 v130, s[48:49]
	s_barrier
	s_waitcnt lgkmcnt(0)
	s_waitcnt lgkmcnt(0)
	v_mfma_f32_16x16x32_bf16 v[118:121], v[228:231], v[172:175], v[118:121]
	v_mfma_f32_16x16x32_bf16 v[114:117], v[236:239], v[172:175], v[114:117]
	v_mfma_f32_16x16x32_bf16 v[102:105], v[228:231], v[180:183], v[102:105]
	v_mfma_f32_16x16x32_bf16 v[98:101], v[236:239], v[180:183], v[98:101]
	v_mfma_f32_16x16x32_bf16 v[86:89], v[228:231], v[188:191], v[86:89]
	v_mfma_f32_16x16x32_bf16 v[82:85], v[236:239], v[188:191], v[82:85]
	v_mfma_f32_16x16x32_bf16 v[70:73], v[228:231], v[196:199], v[70:73]
	v_mfma_f32_16x16x32_bf16 v[66:69], v[236:239], v[196:199], v[66:69]
	v_mfma_f32_16x16x32_bf16 v[118:121], v[232:235], v[176:179], v[118:121]
	v_mfma_f32_16x16x32_bf16 v[114:117], v[240:243], v[176:179], v[114:117]
	v_mfma_f32_16x16x32_bf16 v[102:105], v[232:235], v[184:187], v[102:105]
	v_mfma_f32_16x16x32_bf16 v[98:101], v[240:243], v[184:187], v[98:101]
	v_mfma_f32_16x16x32_bf16 v[86:89], v[232:235], v[192:195], v[86:89]
	v_mfma_f32_16x16x32_bf16 v[82:85], v[240:243], v[192:195], v[82:85]
	v_mfma_f32_16x16x32_bf16 v[70:73], v[232:235], v[224:227], v[70:73]
	v_mfma_f32_16x16x32_bf16 v[66:69], v[240:243], v[224:227], v[66:69]
	s_mov_b32 m0, s53
	s_add_u32 s78, s50, s94
	s_addc_u32 s79, s51, s95
	s_barrier
	ds_read_b128 v[172:175], v155 offset:16384
	ds_read_b128 v[176:179], v155 offset:17408
	ds_read_b128 v[180:183], v155 offset:18432
	ds_read_b128 v[184:187], v155 offset:19456
	ds_read_b128 v[188:191], v155 offset:20480
	ds_read_b128 v[192:195], v155 offset:21504
	ds_read_b128 v[196:199], v155 offset:22528
	ds_read_b128 v[224:227], v155 offset:23552
	global_load_lds_dwordx4 v134, s[50:51]
	s_mov_b32 m0, s54
	s_nop 0
	global_load_lds_dwordx4 v132, s[50:51]
	s_barrier
	s_waitcnt lgkmcnt(0)
	s_waitcnt lgkmcnt(0)
	v_mfma_f32_16x16x32_bf16 v[62:65], v[140:143], v[172:175], v[62:65]
	v_mfma_f32_16x16x32_bf16 v[58:61], v[148:151], v[172:175], v[58:61]
	v_mfma_f32_16x16x32_bf16 v[46:49], v[140:143], v[180:183], v[46:49]
	v_mfma_f32_16x16x32_bf16 v[42:45], v[148:151], v[180:183], v[42:45]
	v_mfma_f32_16x16x32_bf16 v[30:33], v[140:143], v[188:191], v[30:33]
	v_mfma_f32_16x16x32_bf16 v[26:29], v[148:151], v[188:191], v[26:29]
	v_mfma_f32_16x16x32_bf16 v[14:17], v[140:143], v[196:199], v[14:17]
	v_mfma_f32_16x16x32_bf16 v[10:13], v[148:151], v[196:199], v[10:13]
	v_mfma_f32_16x16x32_bf16 v[62:65], v[144:147], v[176:179], v[62:65]
	v_mfma_f32_16x16x32_bf16 v[58:61], v[168:171], v[176:179], v[58:61]
	v_mfma_f32_16x16x32_bf16 v[46:49], v[144:147], v[184:187], v[46:49]
	v_mfma_f32_16x16x32_bf16 v[42:45], v[168:171], v[184:187], v[42:45]
	v_mfma_f32_16x16x32_bf16 v[30:33], v[144:147], v[192:195], v[30:33]
	v_mfma_f32_16x16x32_bf16 v[26:29], v[168:171], v[192:195], v[26:29]
	v_mfma_f32_16x16x32_bf16 v[14:17], v[144:147], v[224:227], v[14:17]
	v_mfma_f32_16x16x32_bf16 v[10:13], v[168:171], v[224:227], v[10:13]
	s_barrier
	s_add_u32 s0, s48, 0x160000
	s_addc_u32 s1, s49, 0
	s_add_i32 s70, s71, s52
	s_mov_b32 m0, s70
	s_nop 0
	global_load_lds_dwordx4 v0, s[0:1]
	s_add_i32 m0, s70, 0x2000
	s_nop 0
	global_load_lds_dwordx4 v130, s[0:1]
	s_waitcnt vmcnt(6)
	s_barrier
	v_mfma_f32_16x16x32_bf16 v[54:57], v[228:231], v[172:175], v[54:57]
	v_mfma_f32_16x16x32_bf16 v[50:53], v[236:239], v[172:175], v[50:53]
	v_mfma_f32_16x16x32_bf16 v[38:41], v[228:231], v[180:183], v[38:41]
	v_mfma_f32_16x16x32_bf16 v[34:37], v[236:239], v[180:183], v[34:37]
	v_mfma_f32_16x16x32_bf16 v[22:25], v[228:231], v[188:191], v[22:25]
	v_mfma_f32_16x16x32_bf16 v[18:21], v[236:239], v[188:191], v[18:21]
	v_mfma_f32_16x16x32_bf16 v[6:9], v[228:231], v[196:199], v[6:9]
	v_mfma_f32_16x16x32_bf16 v[2:5], v[236:239], v[196:199], v[2:5]
	v_mfma_f32_16x16x32_bf16 v[54:57], v[232:235], v[176:179], v[54:57]
	v_mfma_f32_16x16x32_bf16 v[50:53], v[240:243], v[176:179], v[50:53]
	v_mfma_f32_16x16x32_bf16 v[38:41], v[232:235], v[184:187], v[38:41]
	v_mfma_f32_16x16x32_bf16 v[34:37], v[240:243], v[184:187], v[34:37]
	v_mfma_f32_16x16x32_bf16 v[22:25], v[232:235], v[192:195], v[22:25]
	v_mfma_f32_16x16x32_bf16 v[18:21], v[240:243], v[192:195], v[18:21]
	v_mfma_f32_16x16x32_bf16 v[6:9], v[232:235], v[224:227], v[6:9]
	v_mfma_f32_16x16x32_bf16 v[2:5], v[240:243], v[224:227], v[2:5]
	s_add_i32 s70, 0, 0x18000
	s_barrier
	ds_read_b128 v[140:143], v153 offset:32768
	ds_read_b128 v[144:147], v153 offset:33792
	ds_read_b128 v[148:151], v153 offset:34816
	ds_read_b128 v[168:171], v153 offset:35840
	s_add_u32 s0, s50, 0x2c0000
	s_addc_u32 s1, s51, 0
	s_mov_b32 m0, s55
	ds_read_b128 v[172:175], v155 offset:32768
	ds_read_b128 v[176:179], v155 offset:33792
	ds_read_b128 v[180:183], v155 offset:34816
	ds_read_b128 v[184:187], v155 offset:35840
	ds_read_b128 v[188:191], v155 offset:36864
	ds_read_b128 v[192:195], v155 offset:37888
	ds_read_b128 v[196:199], v155 offset:38912
	ds_read_b128 v[224:227], v155 offset:39936
	global_load_lds_dwordx4 v134, s[0:1]
	s_mov_b32 m0, s56
	s_nop 0
	global_load_lds_dwordx4 v132, s[0:1]
	s_waitcnt lgkmcnt(8)
	s_barrier
	s_waitcnt lgkmcnt(0)
	s_waitcnt lgkmcnt(0)
	v_mfma_f32_16x16x32_bf16 v[126:129], v[140:143], v[172:175], v[126:129]
	v_mfma_f32_16x16x32_bf16 v[122:125], v[148:151], v[172:175], v[122:125]
	v_mfma_f32_16x16x32_bf16 v[110:113], v[140:143], v[180:183], v[110:113]
	v_mfma_f32_16x16x32_bf16 v[106:109], v[148:151], v[180:183], v[106:109]
	v_mfma_f32_16x16x32_bf16 v[94:97], v[140:143], v[188:191], v[94:97]
	v_mfma_f32_16x16x32_bf16 v[90:93], v[148:151], v[188:191], v[90:93]
	v_mfma_f32_16x16x32_bf16 v[78:81], v[140:143], v[196:199], v[78:81]
	v_mfma_f32_16x16x32_bf16 v[74:77], v[148:151], v[196:199], v[74:77]
	v_mfma_f32_16x16x32_bf16 v[126:129], v[144:147], v[176:179], v[126:129]
	v_mfma_f32_16x16x32_bf16 v[122:125], v[168:171], v[176:179], v[122:125]
	v_mfma_f32_16x16x32_bf16 v[110:113], v[144:147], v[184:187], v[110:113]
	v_mfma_f32_16x16x32_bf16 v[106:109], v[168:171], v[184:187], v[106:109]
	v_mfma_f32_16x16x32_bf16 v[94:97], v[144:147], v[192:195], v[94:97]
	v_mfma_f32_16x16x32_bf16 v[90:93], v[168:171], v[192:195], v[90:93]
	v_mfma_f32_16x16x32_bf16 v[78:81], v[144:147], v[224:227], v[78:81]
	v_mfma_f32_16x16x32_bf16 v[74:77], v[168:171], v[224:227], v[74:77]
	s_barrier
	s_add_i32 s50, 0, 0x1c000
	s_add_i32 s0, s70, s52
	s_mov_b32 m0, s0
	ds_read_b128 v[228:231], v153 offset:49152
	ds_read_b128 v[232:235], v153 offset:50176
	ds_read_b128 v[236:239], v153 offset:51200
	ds_read_b128 v[240:243], v153 offset:52224
	global_load_lds_dwordx4 v0, s[76:77]
	s_add_i32 m0, s0, 0x2000
	s_nop 0
	global_load_lds_dwordx4 v130, s[76:77]
	s_barrier
	s_waitcnt lgkmcnt(0)
	s_waitcnt lgkmcnt(0)
	v_mfma_f32_16x16x32_bf16 v[118:121], v[228:231], v[172:175], v[118:121]
	v_mfma_f32_16x16x32_bf16 v[114:117], v[236:239], v[172:175], v[114:117]
	v_mfma_f32_16x16x32_bf16 v[102:105], v[228:231], v[180:183], v[102:105]
	v_mfma_f32_16x16x32_bf16 v[98:101], v[236:239], v[180:183], v[98:101]
	v_mfma_f32_16x16x32_bf16 v[86:89], v[228:231], v[188:191], v[86:89]
	v_mfma_f32_16x16x32_bf16 v[82:85], v[236:239], v[188:191], v[82:85]
	v_mfma_f32_16x16x32_bf16 v[70:73], v[228:231], v[196:199], v[70:73]
	v_mfma_f32_16x16x32_bf16 v[66:69], v[236:239], v[196:199], v[66:69]
	v_mfma_f32_16x16x32_bf16 v[118:121], v[232:235], v[176:179], v[118:121]
	v_mfma_f32_16x16x32_bf16 v[114:117], v[240:243], v[176:179], v[114:117]
	v_mfma_f32_16x16x32_bf16 v[102:105], v[232:235], v[184:187], v[102:105]
	v_mfma_f32_16x16x32_bf16 v[98:101], v[240:243], v[184:187], v[98:101]
	v_mfma_f32_16x16x32_bf16 v[86:89], v[232:235], v[192:195], v[86:89]
	v_mfma_f32_16x16x32_bf16 v[82:85], v[240:243], v[192:195], v[82:85]
	v_mfma_f32_16x16x32_bf16 v[70:73], v[232:235], v[224:227], v[70:73]
	v_mfma_f32_16x16x32_bf16 v[66:69], v[240:243], v[224:227], v[66:69]
	s_mov_b32 m0, s57
	s_barrier
	ds_read_b128 v[172:175], v155 offset:49152
	ds_read_b128 v[176:179], v155 offset:50176
	ds_read_b128 v[180:183], v155 offset:51200
	ds_read_b128 v[184:187], v155 offset:52224
	ds_read_b128 v[188:191], v155 offset:53248
	ds_read_b128 v[192:195], v155 offset:54272
	ds_read_b128 v[196:199], v155 offset:55296
	ds_read_b128 v[224:227], v155 offset:56320
	global_load_lds_dwordx4 v134, s[78:79]
	s_mov_b32 m0, s58
	s_nop 0
	global_load_lds_dwordx4 v132, s[78:79]
	s_barrier
	s_waitcnt lgkmcnt(0)
	s_waitcnt lgkmcnt(0)
	v_mfma_f32_16x16x32_bf16 v[62:65], v[140:143], v[172:175], v[62:65]
	v_mfma_f32_16x16x32_bf16 v[58:61], v[148:151], v[172:175], v[58:61]
	v_mfma_f32_16x16x32_bf16 v[46:49], v[140:143], v[180:183], v[46:49]
	v_mfma_f32_16x16x32_bf16 v[42:45], v[148:151], v[180:183], v[42:45]
	v_mfma_f32_16x16x32_bf16 v[30:33], v[140:143], v[188:191], v[30:33]
	v_mfma_f32_16x16x32_bf16 v[26:29], v[148:151], v[188:191], v[26:29]
	v_mfma_f32_16x16x32_bf16 v[14:17], v[140:143], v[196:199], v[14:17]
	v_mfma_f32_16x16x32_bf16 v[10:13], v[148:151], v[196:199], v[10:13]
	v_mfma_f32_16x16x32_bf16 v[62:65], v[144:147], v[176:179], v[62:65]
	v_mfma_f32_16x16x32_bf16 v[58:61], v[168:171], v[176:179], v[58:61]
	v_mfma_f32_16x16x32_bf16 v[46:49], v[144:147], v[184:187], v[46:49]
	v_mfma_f32_16x16x32_bf16 v[42:45], v[168:171], v[184:187], v[42:45]
	v_mfma_f32_16x16x32_bf16 v[30:33], v[144:147], v[192:195], v[30:33]
	v_mfma_f32_16x16x32_bf16 v[26:29], v[168:171], v[192:195], v[26:29]
	v_mfma_f32_16x16x32_bf16 v[14:17], v[144:147], v[224:227], v[14:17]
	v_mfma_f32_16x16x32_bf16 v[10:13], v[168:171], v[224:227], v[10:13]
	s_barrier
	s_add_u32 s0, s48, 0x160080
	s_addc_u32 s1, s49, 0
	s_add_i32 s48, s50, s52
	s_mov_b32 m0, s48
	s_nop 0
	global_load_lds_dwordx4 v0, s[0:1]
	s_add_i32 m0, s48, 0x2000
	s_nop 0
	global_load_lds_dwordx4 v130, s[0:1]
	s_waitcnt vmcnt(6)
	s_barrier
	v_mfma_f32_16x16x32_bf16 v[54:57], v[228:231], v[172:175], v[54:57]
	v_mfma_f32_16x16x32_bf16 v[50:53], v[236:239], v[172:175], v[50:53]
	v_mfma_f32_16x16x32_bf16 v[38:41], v[228:231], v[180:183], v[38:41]
	v_mfma_f32_16x16x32_bf16 v[34:37], v[236:239], v[180:183], v[34:37]
	v_mfma_f32_16x16x32_bf16 v[22:25], v[228:231], v[188:191], v[22:25]
	v_mfma_f32_16x16x32_bf16 v[18:21], v[236:239], v[188:191], v[18:21]
	v_mfma_f32_16x16x32_bf16 v[6:9], v[228:231], v[196:199], v[6:9]
	v_mfma_f32_16x16x32_bf16 v[2:5], v[236:239], v[196:199], v[2:5]
	v_mfma_f32_16x16x32_bf16 v[54:57], v[232:235], v[176:179], v[54:57]
	v_mfma_f32_16x16x32_bf16 v[50:53], v[240:243], v[176:179], v[50:53]
	v_mfma_f32_16x16x32_bf16 v[38:41], v[232:235], v[184:187], v[38:41]
	v_mfma_f32_16x16x32_bf16 v[34:37], v[240:243], v[184:187], v[34:37]
	v_mfma_f32_16x16x32_bf16 v[22:25], v[232:235], v[192:195], v[22:25]
	v_mfma_f32_16x16x32_bf16 v[18:21], v[240:243], v[192:195], v[18:21]
	v_mfma_f32_16x16x32_bf16 v[6:9], v[232:235], v[224:227], v[6:9]
	v_mfma_f32_16x16x32_bf16 v[2:5], v[240:243], v[224:227], v[2:5]
	s_add_u32 s13, s13, 0x100
	s_addc_u32 s68, s68, 0
	s_cmp_ge_i32 s69, s39
	s_mov_b64 s[0:1], s[46:47]
	s_mov_b32 s48, s69
	s_barrier
	s_cbranch_scc0 .LBB0_37
	s_cmp_eq_u32 s65, 2
	s_cbranch_scc1 .Lepi10_orig
	v_readlane_b32 s90, v255, 17
	v_readlane_b32 s91, v255, 18
	v_readlane_b32 s96, v255, 19
	v_readlane_b32 s97, v255, 20
	v_lshl_or_b32 v156, s66, 8, v154
	v_lshlrev_b32_e32 v156, 2, v156
	v_lshl_add_u32 v157, v152, 13, v156
	s_lshl_b32 s72, s67, 21
	s_add_u32 s74, s22, s72
	s_addc_u32 s75, s23, 0
	s_add_u32 s76, s22, s72
	s_addc_u32 s77, s23, 0
	s_lshr_b32 s73, s67, 3
	s_mul_i32 s73, s73, 0xc000
	s_add_u32 s73, s73, 0xa000
	s_add_u32 s70, s90, s73
	s_addc_u32 s71, s91, 0
	global_load_dwordx4 v[140:143], v156, s[70:71]
	global_load_dwordx4 v[144:147], v156, s[70:71] offset:64
	global_load_dwordx4 v[148:151], v156, s[70:71] offset:512
	global_load_dwordx4 v[168:171], v156, s[70:71] offset:576
	global_load_dwordx4 v[224:227], v157, s[74:75] nt
	global_load_dwordx4 v[228:231], v157, s[74:75] offset:64 nt
	global_load_dwordx4 v[232:235], v157, s[74:75] offset:512 nt
	global_load_dwordx4 v[236:239], v157, s[74:75] offset:576 nt
	s_add_u32 s74, s74, 0x20000
	s_addc_u32 s75, s75, 0
	global_load_dwordx4 v[240:243], v157, s[74:75] nt
	global_load_dwordx4 v[244:247], v157, s[74:75] offset:64 nt
	s_waitcnt vmcnt(5)
	v_pk_fma_f32 v[128:129], v[128:129], v[142:143], v[226:227]
	v_pk_fma_f32 v[126:127], v[126:127], v[140:141], v[224:225]
	global_store_dwordx4 v157, v[126:129], s[76:77] nt
	global_load_dwordx4 v[224:227], v157, s[74:75] offset:512 nt
	s_waitcnt vmcnt(6)
	v_pk_fma_f32 v[124:125], v[124:125], v[146:147], v[230:231]
	v_pk_fma_f32 v[122:123], v[122:123], v[144:145], v[228:229]
	global_store_dwordx4 v157, v[122:125], s[76:77] offset:64 nt
	global_load_dwordx4 v[228:231], v157, s[74:75] offset:576 nt
	s_waitcnt vmcnt(7)
	v_pk_fma_f32 v[120:121], v[120:121], v[150:151], v[234:235]
	v_pk_fma_f32 v[118:119], v[118:119], v[148:149], v[232:233]
	global_store_dwordx4 v157, v[118:121], s[76:77] offset:512 nt
	s_add_u32 s74, s74, 0x20000
	s_addc_u32 s75, s75, 0
	global_load_dwordx4 v[232:235], v157, s[74:75] nt
	s_waitcnt vmcnt(8)
	v_pk_fma_f32 v[116:117], v[116:117], v[170:171], v[238:239]
	v_pk_fma_f32 v[114:115], v[114:115], v[168:169], v[236:237]
	global_store_dwordx4 v157, v[114:117], s[76:77] offset:576 nt
	global_load_dwordx4 v[236:239], v157, s[74:75] offset:64 nt
	s_add_u32 s76, s76, 0x20000
	s_addc_u32 s77, s77, 0
	s_waitcnt vmcnt(9)
	v_pk_fma_f32 v[112:113], v[112:113], v[142:143], v[242:243]
	v_pk_fma_f32 v[110:111], v[110:111], v[140:141], v[240:241]
	global_store_dwordx4 v157, v[110:113], s[76:77] nt
	global_load_dwordx4 v[240:243], v157, s[74:75] offset:512 nt
	s_waitcnt vmcnt(10)
	v_pk_fma_f32 v[108:109], v[108:109], v[146:147], v[246:247]
	v_pk_fma_f32 v[106:107], v[106:107], v[144:145], v[244:245]
	global_store_dwordx4 v157, v[106:109], s[76:77] offset:64 nt
	global_load_dwordx4 v[244:247], v157, s[74:75] offset:576 nt
	s_waitcnt vmcnt(10)
	v_pk_fma_f32 v[104:105], v[104:105], v[150:151], v[226:227]
	v_pk_fma_f32 v[102:103], v[102:103], v[148:149], v[224:225]
	global_store_dwordx4 v157, v[102:105], s[76:77] offset:512 nt
	s_add_u32 s74, s74, 0x20000
	s_addc_u32 s75, s75, 0
	global_load_dwordx4 v[224:227], v157, s[74:75] nt
	s_waitcnt vmcnt(10)
	v_pk_fma_f32 v[100:101], v[100:101], v[170:171], v[230:231]
	v_pk_fma_f32 v[98:99], v[98:99], v[168:169], v[228:229]
	global_store_dwordx4 v157, v[98:101], s[76:77] offset:576 nt
	global_load_dwordx4 v[228:231], v157, s[74:75] offset:64 nt
	s_add_u32 s76, s76, 0x20000
	s_addc_u32 s77, s77, 0
	s_waitcnt vmcnt(10)
	v_pk_fma_f32 v[96:97], v[96:97], v[142:143], v[234:235]
	v_pk_fma_f32 v[94:95], v[94:95], v[140:141], v[232:233]
	global_store_dwordx4 v157, v[94:97], s[76:77] nt
	global_load_dwordx4 v[232:235], v157, s[74:75] offset:512 nt
	s_waitcnt vmcnt(10)
	v_pk_fma_f32 v[92:93], v[92:93], v[146:147], v[238:239]
	v_pk_fma_f32 v[90:91], v[90:91], v[144:145], v[236:237]
	global_store_dwordx4 v157, v[90:93], s[76:77] offset:64 nt
	global_load_dwordx4 v[236:239], v157, s[74:75] offset:576 nt
	s_waitcnt vmcnt(10)
	v_pk_fma_f32 v[88:89], v[88:89], v[150:151], v[242:243]
	v_pk_fma_f32 v[86:87], v[86:87], v[148:149], v[240:241]
	global_store_dwordx4 v157, v[86:89], s[76:77] offset:512 nt
	s_add_u32 s74, s74, 0xa0000
	s_addc_u32 s75, s75, 0
	global_load_dwordx4 v[240:243], v157, s[74:75] nt
	s_waitcnt vmcnt(10)
	v_pk_fma_f32 v[84:85], v[84:85], v[170:171], v[246:247]
	v_pk_fma_f32 v[82:83], v[82:83], v[168:169], v[244:245]
	global_store_dwordx4 v157, v[82:85], s[76:77] offset:576 nt
	global_load_dwordx4 v[244:247], v157, s[74:75] offset:64 nt
	s_add_u32 s76, s76, 0x20000
	s_addc_u32 s77, s77, 0
	s_waitcnt vmcnt(10)
	v_pk_fma_f32 v[80:81], v[80:81], v[142:143], v[226:227]
	v_pk_fma_f32 v[78:79], v[78:79], v[140:141], v[224:225]
	global_store_dwordx4 v157, v[78:81], s[76:77] nt
	global_load_dwordx4 v[224:227], v157, s[74:75] offset:512 nt
	s_waitcnt vmcnt(10)
	v_pk_fma_f32 v[76:77], v[76:77], v[146:147], v[230:231]
	v_pk_fma_f32 v[74:75], v[74:75], v[144:145], v[228:229]
	global_store_dwordx4 v157, v[74:77], s[76:77] offset:64 nt
	global_load_dwordx4 v[228:231], v157, s[74:75] offset:576 nt
	s_waitcnt vmcnt(10)
	v_pk_fma_f32 v[72:73], v[72:73], v[150:151], v[234:235]
	v_pk_fma_f32 v[70:71], v[70:71], v[148:149], v[232:233]
	global_store_dwordx4 v157, v[70:73], s[76:77] offset:512 nt
	s_add_u32 s74, s74, 0x20000
	s_addc_u32 s75, s75, 0
	global_load_dwordx4 v[232:235], v157, s[74:75] nt
	s_waitcnt vmcnt(10)
	v_pk_fma_f32 v[68:69], v[68:69], v[170:171], v[238:239]
	v_pk_fma_f32 v[66:67], v[66:67], v[168:169], v[236:237]
	global_store_dwordx4 v157, v[66:69], s[76:77] offset:576 nt
	global_load_dwordx4 v[236:239], v157, s[74:75] offset:64 nt
	s_add_u32 s76, s76, 0xa0000
	s_addc_u32 s77, s77, 0
	s_waitcnt vmcnt(10)
	v_pk_fma_f32 v[64:65], v[64:65], v[142:143], v[242:243]
	v_pk_fma_f32 v[62:63], v[62:63], v[140:141], v[240:241]
	global_store_dwordx4 v157, v[62:65], s[76:77] nt
	global_load_dwordx4 v[240:243], v157, s[74:75] offset:512 nt
	s_waitcnt vmcnt(10)
	v_pk_fma_f32 v[60:61], v[60:61], v[146:147], v[246:247]
	v_pk_fma_f32 v[58:59], v[58:59], v[144:145], v[244:245]
	global_store_dwordx4 v157, v[58:61], s[76:77] offset:64 nt
	global_load_dwordx4 v[244:247], v157, s[74:75] offset:576 nt
	s_waitcnt vmcnt(10)
	v_pk_fma_f32 v[56:57], v[56:57], v[150:151], v[226:227]
	v_pk_fma_f32 v[54:55], v[54:55], v[148:149], v[224:225]
	global_store_dwordx4 v157, v[54:57], s[76:77] offset:512 nt
	s_add_u32 s74, s74, 0x20000
	s_addc_u32 s75, s75, 0
	global_load_dwordx4 v[224:227], v157, s[74:75] nt
	s_waitcnt vmcnt(10)
	v_pk_fma_f32 v[52:53], v[52:53], v[170:171], v[230:231]
	v_pk_fma_f32 v[50:51], v[50:51], v[168:169], v[228:229]
	global_store_dwordx4 v157, v[50:53], s[76:77] offset:576 nt
	global_load_dwordx4 v[228:231], v157, s[74:75] offset:64 nt
	s_add_u32 s76, s76, 0x20000
	s_addc_u32 s77, s77, 0
	s_waitcnt vmcnt(10)
	v_pk_fma_f32 v[48:49], v[48:49], v[142:143], v[234:235]
	v_pk_fma_f32 v[46:47], v[46:47], v[140:141], v[232:233]
	global_store_dwordx4 v157, v[46:49], s[76:77] nt
	global_load_dwordx4 v[232:235], v157, s[74:75] offset:512 nt
	s_waitcnt vmcnt(10)
	v_pk_fma_f32 v[44:45], v[44:45], v[146:147], v[238:239]
	v_pk_fma_f32 v[42:43], v[42:43], v[144:145], v[236:237]
	global_store_dwordx4 v157, v[42:45], s[76:77] offset:64 nt
	global_load_dwordx4 v[236:239], v157, s[74:75] offset:576 nt
	s_waitcnt vmcnt(10)
	v_pk_fma_f32 v[40:41], v[40:41], v[150:151], v[242:243]
	v_pk_fma_f32 v[38:39], v[38:39], v[148:149], v[240:241]
	global_store_dwordx4 v157, v[38:41], s[76:77] offset:512 nt
	s_add_u32 s74, s74, 0x20000
	s_addc_u32 s75, s75, 0
	global_load_dwordx4 v[240:243], v157, s[74:75] nt
	s_waitcnt vmcnt(10)
	v_pk_fma_f32 v[36:37], v[36:37], v[170:171], v[246:247]
	v_pk_fma_f32 v[34:35], v[34:35], v[168:169], v[244:245]
	global_store_dwordx4 v157, v[34:37], s[76:77] offset:576 nt
	global_load_dwordx4 v[244:247], v157, s[74:75] offset:64 nt
	s_add_u32 s76, s76, 0x20000
	s_addc_u32 s77, s77, 0
	s_waitcnt vmcnt(10)
	v_pk_fma_f32 v[32:33], v[32:33], v[142:143], v[226:227]
	v_pk_fma_f32 v[30:31], v[30:31], v[140:141], v[224:225]
	global_store_dwordx4 v157, v[30:33], s[76:77] nt
	global_load_dwordx4 v[224:227], v157, s[74:75] offset:512 nt
	s_waitcnt vmcnt(10)
	v_pk_fma_f32 v[28:29], v[28:29], v[146:147], v[230:231]
	v_pk_fma_f32 v[26:27], v[26:27], v[144:145], v[228:229]
	global_store_dwordx4 v157, v[26:29], s[76:77] offset:64 nt
	global_load_dwordx4 v[228:231], v157, s[74:75] offset:576 nt
	s_waitcnt vmcnt(10)
	v_pk_fma_f32 v[24:25], v[24:25], v[150:151], v[234:235]
	v_pk_fma_f32 v[22:23], v[22:23], v[148:149], v[232:233]
	global_store_dwordx4 v157, v[22:25], s[76:77] offset:512 nt
	s_waitcnt vmcnt(9)
	v_pk_fma_f32 v[20:21], v[20:21], v[170:171], v[238:239]
	v_pk_fma_f32 v[18:19], v[18:19], v[168:169], v[236:237]
	global_store_dwordx4 v157, v[18:21], s[76:77] offset:576 nt
	s_add_u32 s76, s76, 0x20000
	s_addc_u32 s77, s77, 0
	s_waitcnt vmcnt(8)
	v_pk_fma_f32 v[16:17], v[16:17], v[142:143], v[242:243]
	v_pk_fma_f32 v[14:15], v[14:15], v[140:141], v[240:241]
	global_store_dwordx4 v157, v[14:17], s[76:77] nt
	s_waitcnt vmcnt(7)
	v_pk_fma_f32 v[12:13], v[12:13], v[146:147], v[246:247]
	v_pk_fma_f32 v[10:11], v[10:11], v[144:145], v[244:245]
	global_store_dwordx4 v157, v[10:13], s[76:77] offset:64 nt
	s_waitcnt vmcnt(6)
	v_pk_fma_f32 v[8:9], v[8:9], v[150:151], v[226:227]
	v_pk_fma_f32 v[6:7], v[6:7], v[148:149], v[224:225]
	global_store_dwordx4 v157, v[6:9], s[76:77] offset:512 nt
	s_waitcnt vmcnt(5)
	v_pk_fma_f32 v[4:5], v[4:5], v[170:171], v[230:231]
	v_pk_fma_f32 v[2:3], v[2:3], v[168:169], v[228:229]
	global_store_dwordx4 v157, v[2:5], s[76:77] offset:576 nt
	s_branch .LBB0_24

.LBB0_226:
	v_readlane_b32 s48, v253, 24
	v_readlane_b32 s49, v253, 25
	v_mov_b32_e32 v131, v1
	v_readlane_b32 s46, v253, 20
	v_lshl_add_u64 v[8:9], s[48:49], 0, v[0:1]
	v_lshl_add_u64 v[10:11], s[48:49], 0, v[130:131]
	v_mov_b32_e32 v135, v1
	v_readlane_b32 s47, v253, 21
	s_add_i32 m0, s53, 0x18000
	v_lshl_add_u64 v[8:9], v[8:9], 0, s[94:95]
	v_lshl_add_u64 v[12:13], s[46:47], 0, v[134:135]
	v_mov_b32_e32 v133, v1
	s_waitcnt vmcnt(4)
	s_barrier
	global_load_lds_dwordx4 v[8:9], off
	v_lshl_add_u64 v[8:9], v[10:11], 0, s[94:95]
	s_add_i32 m0, s53, 0x1a000
	s_add_i32 s57, s53, 0x8000
	v_lshl_add_u64 v[14:15], s[46:47], 0, v[132:133]
	global_load_lds_dwordx4 v[8:9], off
	v_lshl_add_u64 v[8:9], v[12:13], 0, s[94:95]
	s_mov_b32 m0, s57
	s_add_i32 s58, s53, 0xa000
	v_readlane_b32 s12, v253, 26
	global_load_lds_dwordx4 v[8:9], off
	v_lshl_add_u64 v[8:9], v[14:15], 0, s[94:95]
	s_mov_b32 m0, s58
	v_readlane_b32 s13, v253, 27
	global_load_lds_dwordx4 v[8:9], off
	s_add_i32 m0, s53, 0x1c000
	v_lshl_add_u64 v[8:9], s[12:13], 0, v[0:1]
	global_load_lds_dwordx4 v[8:9], off
	v_lshl_add_u64 v[8:9], s[12:13], 0, v[130:131]
	s_add_i32 m0, s53, 0x1e000
	v_lshrrev_b32_e32 v17, 1, v166
	global_load_lds_dwordx4 v[8:9], off
	v_and_b32_e32 v17, 24, v17
	v_lshlrev_b32_e32 v8, 15, v6
	v_and_b32_e32 v16, 15, v166
	v_lshlrev_b32_e32 v18, 1, v17
	v_and_b32_e32 v8, 0xffff0000, v8
	v_lshl_or_b32 v140, s1, 6, v16
	v_lshl_or_b32 v16, v16, 6, v18
	v_lshlrev_b32_e32 v18, 2, v166
	s_lshl_b32 s0, s0, 5
	v_lshl_add_u32 v5, v5, 12, v8
	v_and_b32_e32 v6, 1, v6
	s_lshl_b32 s1, s1, 13
	v_and_b32_e32 v18, 32, v18
	s_and_b32 s0, s0, 0x60
	v_lshl_or_b32 v5, v6, 6, v5
	v_bitop3_b32 v19, v16, s1, v18 bitop3:0xde
	s_lshl_b32 s1, s0, 7
	v_lshl_add_u32 v136, v7, 1, v5
	v_lshlrev_b32_e32 v5, 15, v2
	v_bitop3_b32 v141, s1, v16, v18 bitop3:0xf6
	v_add_u32_e32 v141, 0x10000, v141
	v_or_b32_e32 v142, s0, v17
	v_and_b32_e32 v5, 0xffff0000, v5
	v_readlane_b32 s0, v253, 14
	s_waitcnt vmcnt(6)
	v_lshl_add_u32 v3, v3, 12, v5
	v_and_b32_e32 v2, 1, v2
	v_readlane_b32 s1, v253, 15
	v_lshl_or_b32 v2, v2, 6, v3
	s_mov_b32 s60, s0
	v_readlane_b32 s0, v253, 12
	v_mov_b32_e32 v137, v1
	v_lshl_add_u32 v138, v4, 1, v2
	v_mov_b32_e32 v139, v1
	s_mov_b32 s59, 0
	v_add_u32_e32 v143, 0, v19
	s_mov_b32 s61, s0
	s_barrier
	v_readlane_b32 s1, v253, 13

.LBB0_234:
	s_add_u32 s39, s46, 0xfff80080
	s_addc_u32 s48, s47, -1
	s_add_i32 s62, 0, 0x10000
	ds_read_b128 v[144:147], v141
	ds_read_b128 v[148:151], v141 offset:1024
	ds_read_b128 v[152:155], v141 offset:2048
	ds_read_b128 v[168:171], v141 offset:3072
	s_cmp_eq_u32 s13, 28
	s_cselect_b32 s51, s43, s48
	s_cselect_b32 s50, s42, s39
	s_cselect_b32 s49, s45, s12
	s_cselect_b32 s48, s44, s1
	s_add_i32 m0, s53, 0xc000
	ds_read_b128 v[172:175], v143
	ds_read_b128 v[176:179], v143 offset:1024
	ds_read_b128 v[180:183], v143 offset:2048
	ds_read_b128 v[184:187], v143 offset:3072
	ds_read_b128 v[188:191], v143 offset:4096
	ds_read_b128 v[192:195], v143 offset:5120
	ds_read_b128 v[196:199], v143 offset:6144
	ds_read_b128 v[224:227], v143 offset:7168
	global_load_lds_dwordx4 v136, s[46:47]
	s_add_i32 m0, s53, 0xe000
	s_nop 0
	global_load_lds_dwordx4 v138, s[46:47]
	s_waitcnt lgkmcnt(8)
	s_barrier
	s_waitcnt lgkmcnt(0)
	s_waitcnt lgkmcnt(0)
	v_mfma_f32_16x16x32_bf16 v[126:129], v[144:147], v[172:175], v[126:129]
	v_mfma_f32_16x16x32_bf16 v[122:125], v[152:155], v[172:175], v[122:125]
	v_mfma_f32_16x16x32_bf16 v[118:121], v[144:147], v[180:183], v[118:121]
	v_mfma_f32_16x16x32_bf16 v[114:117], v[152:155], v[180:183], v[114:117]
	v_mfma_f32_16x16x32_bf16 v[102:105], v[144:147], v[188:191], v[102:105]
	v_mfma_f32_16x16x32_bf16 v[98:101], v[152:155], v[188:191], v[98:101]
	v_mfma_f32_16x16x32_bf16 v[86:89], v[144:147], v[196:199], v[86:89]
	v_mfma_f32_16x16x32_bf16 v[82:85], v[152:155], v[196:199], v[82:85]
	v_mfma_f32_16x16x32_bf16 v[126:129], v[148:151], v[176:179], v[126:129]
	v_mfma_f32_16x16x32_bf16 v[122:125], v[168:171], v[176:179], v[122:125]
	v_mfma_f32_16x16x32_bf16 v[118:121], v[148:151], v[184:187], v[118:121]
	v_mfma_f32_16x16x32_bf16 v[114:117], v[168:171], v[184:187], v[114:117]
	v_mfma_f32_16x16x32_bf16 v[102:105], v[148:151], v[192:195], v[102:105]
	v_mfma_f32_16x16x32_bf16 v[98:101], v[168:171], v[192:195], v[98:101]
	v_mfma_f32_16x16x32_bf16 v[86:89], v[148:151], v[224:227], v[86:89]
	v_mfma_f32_16x16x32_bf16 v[82:85], v[168:171], v[224:227], v[82:85]
	s_barrier
	s_add_i32 s39, 0, 0x14000
	s_add_i32 s62, s62, s52
	ds_read_b128 v[228:231], v141 offset:16384
	ds_read_b128 v[232:235], v141 offset:17408
	ds_read_b128 v[236:239], v141 offset:18432
	ds_read_b128 v[240:243], v141 offset:19456
	s_add_u32 s76, s48, s94
	s_addc_u32 s77, s49, s95
	s_mov_b32 m0, s62
	s_nop 0
	global_load_lds_dwordx4 v0, s[48:49]
	s_add_i32 m0, s62, 0x2000
	s_nop 0
	global_load_lds_dwordx4 v130, s[48:49]
	s_barrier
	s_waitcnt lgkmcnt(0)
	s_waitcnt lgkmcnt(0)
	v_mfma_f32_16x16x32_bf16 v[110:113], v[228:231], v[172:175], v[110:113]
	v_mfma_f32_16x16x32_bf16 v[106:109], v[236:239], v[172:175], v[106:109]
	v_mfma_f32_16x16x32_bf16 v[94:97], v[228:231], v[180:183], v[94:97]
	v_mfma_f32_16x16x32_bf16 v[90:93], v[236:239], v[180:183], v[90:93]
	v_mfma_f32_16x16x32_bf16 v[78:81], v[228:231], v[188:191], v[78:81]
	v_mfma_f32_16x16x32_bf16 v[74:77], v[236:239], v[188:191], v[74:77]
	v_mfma_f32_16x16x32_bf16 v[70:73], v[228:231], v[196:199], v[70:73]
	v_mfma_f32_16x16x32_bf16 v[66:69], v[236:239], v[196:199], v[66:69]
	v_mfma_f32_16x16x32_bf16 v[110:113], v[232:235], v[176:179], v[110:113]
	v_mfma_f32_16x16x32_bf16 v[106:109], v[240:243], v[176:179], v[106:109]
	v_mfma_f32_16x16x32_bf16 v[94:97], v[232:235], v[184:187], v[94:97]
	v_mfma_f32_16x16x32_bf16 v[90:93], v[240:243], v[184:187], v[90:93]
	v_mfma_f32_16x16x32_bf16 v[78:81], v[232:235], v[192:195], v[78:81]
	v_mfma_f32_16x16x32_bf16 v[74:77], v[240:243], v[192:195], v[74:77]
	v_mfma_f32_16x16x32_bf16 v[70:73], v[232:235], v[224:227], v[70:73]
	v_mfma_f32_16x16x32_bf16 v[66:69], v[240:243], v[224:227], v[66:69]
	s_mov_b32 m0, s53
	s_add_u32 s78, s50, s94
	s_addc_u32 s79, s51, s95
	s_barrier
	ds_read_b128 v[172:175], v143 offset:16384
	ds_read_b128 v[176:179], v143 offset:17408
	ds_read_b128 v[180:183], v143 offset:18432
	ds_read_b128 v[184:187], v143 offset:19456
	ds_read_b128 v[188:191], v143 offset:20480
	ds_read_b128 v[192:195], v143 offset:21504
	ds_read_b128 v[196:199], v143 offset:22528
	ds_read_b128 v[224:227], v143 offset:23552
	global_load_lds_dwordx4 v134, s[50:51]
	s_mov_b32 m0, s54
	s_nop 0
	global_load_lds_dwordx4 v132, s[50:51]
	s_barrier
	s_waitcnt lgkmcnt(0)
	s_waitcnt lgkmcnt(0)
	v_mfma_f32_16x16x32_bf16 v[62:65], v[144:147], v[172:175], v[62:65]
	v_mfma_f32_16x16x32_bf16 v[58:61], v[152:155], v[172:175], v[58:61]
	v_mfma_f32_16x16x32_bf16 v[54:57], v[144:147], v[180:183], v[54:57]
	v_mfma_f32_16x16x32_bf16 v[50:53], v[152:155], v[180:183], v[50:53]
	v_mfma_f32_16x16x32_bf16 v[38:41], v[144:147], v[188:191], v[38:41]
	v_mfma_f32_16x16x32_bf16 v[34:37], v[152:155], v[188:191], v[34:37]
	v_mfma_f32_16x16x32_bf16 v[22:25], v[144:147], v[196:199], v[22:25]
	v_mfma_f32_16x16x32_bf16 v[18:21], v[152:155], v[196:199], v[18:21]
	v_mfma_f32_16x16x32_bf16 v[62:65], v[148:151], v[176:179], v[62:65]
	v_mfma_f32_16x16x32_bf16 v[58:61], v[168:171], v[176:179], v[58:61]
	v_mfma_f32_16x16x32_bf16 v[54:57], v[148:151], v[184:187], v[54:57]
	v_mfma_f32_16x16x32_bf16 v[50:53], v[168:171], v[184:187], v[50:53]
	v_mfma_f32_16x16x32_bf16 v[38:41], v[148:151], v[192:195], v[38:41]
	v_mfma_f32_16x16x32_bf16 v[34:37], v[168:171], v[192:195], v[34:37]
	v_mfma_f32_16x16x32_bf16 v[22:25], v[148:151], v[224:227], v[22:25]
	v_mfma_f32_16x16x32_bf16 v[18:21], v[168:171], v[224:227], v[18:21]
	s_barrier
	s_add_u32 s62, s48, 0x80000
	s_addc_u32 s63, s49, 0
	s_add_i32 s39, s39, s52
	s_mov_b32 m0, s39
	s_nop 0
	global_load_lds_dwordx4 v0, s[62:63]
	s_add_i32 m0, s39, 0x2000
	s_nop 0
	global_load_lds_dwordx4 v130, s[62:63]
	s_waitcnt vmcnt(6)
	s_barrier
	v_mfma_f32_16x16x32_bf16 v[46:49], v[228:231], v[172:175], v[46:49]
	v_mfma_f32_16x16x32_bf16 v[42:45], v[236:239], v[172:175], v[42:45]
	v_mfma_f32_16x16x32_bf16 v[30:33], v[228:231], v[180:183], v[30:33]
	v_mfma_f32_16x16x32_bf16 v[26:29], v[236:239], v[180:183], v[26:29]
	v_mfma_f32_16x16x32_bf16 v[14:17], v[228:231], v[188:191], v[14:17]
	v_mfma_f32_16x16x32_bf16 v[10:13], v[236:239], v[188:191], v[10:13]
	v_mfma_f32_16x16x32_bf16 v[6:9], v[228:231], v[196:199], v[6:9]
	v_mfma_f32_16x16x32_bf16 v[2:5], v[236:239], v[196:199], v[2:5]
	v_mfma_f32_16x16x32_bf16 v[46:49], v[232:235], v[176:179], v[46:49]
	v_mfma_f32_16x16x32_bf16 v[42:45], v[240:243], v[176:179], v[42:45]
	v_mfma_f32_16x16x32_bf16 v[30:33], v[232:235], v[184:187], v[30:33]
	v_mfma_f32_16x16x32_bf16 v[26:29], v[240:243], v[184:187], v[26:29]
	v_mfma_f32_16x16x32_bf16 v[14:17], v[232:235], v[192:195], v[14:17]
	v_mfma_f32_16x16x32_bf16 v[10:13], v[240:243], v[192:195], v[10:13]
	v_mfma_f32_16x16x32_bf16 v[6:9], v[232:235], v[224:227], v[6:9]
	v_mfma_f32_16x16x32_bf16 v[2:5], v[240:243], v[224:227], v[2:5]
	s_add_i32 s39, 0, 0x18000
	s_barrier
	ds_read_b128 v[144:147], v141 offset:32768
	ds_read_b128 v[148:151], v141 offset:33792
	ds_read_b128 v[152:155], v141 offset:34816
	ds_read_b128 v[168:171], v141 offset:35840
	s_add_u32 s50, s50, 0x80000
	s_addc_u32 s51, s51, 0
	s_mov_b32 m0, s55
	ds_read_b128 v[172:175], v143 offset:32768
	ds_read_b128 v[176:179], v143 offset:33792
	ds_read_b128 v[180:183], v143 offset:34816
	ds_read_b128 v[184:187], v143 offset:35840
	ds_read_b128 v[188:191], v143 offset:36864
	ds_read_b128 v[192:195], v143 offset:37888
	ds_read_b128 v[196:199], v143 offset:38912
	ds_read_b128 v[224:227], v143 offset:39936
	global_load_lds_dwordx4 v134, s[50:51]
	s_mov_b32 m0, s56
	s_nop 0
	global_load_lds_dwordx4 v132, s[50:51]
	s_waitcnt lgkmcnt(8)
	s_barrier
	s_waitcnt lgkmcnt(0)
	s_waitcnt lgkmcnt(0)
	v_mfma_f32_16x16x32_bf16 v[126:129], v[144:147], v[172:175], v[126:129]
	v_mfma_f32_16x16x32_bf16 v[122:125], v[152:155], v[172:175], v[122:125]
	v_mfma_f32_16x16x32_bf16 v[118:121], v[144:147], v[180:183], v[118:121]
	v_mfma_f32_16x16x32_bf16 v[114:117], v[152:155], v[180:183], v[114:117]
	v_mfma_f32_16x16x32_bf16 v[102:105], v[144:147], v[188:191], v[102:105]
	v_mfma_f32_16x16x32_bf16 v[98:101], v[152:155], v[188:191], v[98:101]
	v_mfma_f32_16x16x32_bf16 v[86:89], v[144:147], v[196:199], v[86:89]
	v_mfma_f32_16x16x32_bf16 v[82:85], v[152:155], v[196:199], v[82:85]
	v_mfma_f32_16x16x32_bf16 v[126:129], v[148:151], v[176:179], v[126:129]
	v_mfma_f32_16x16x32_bf16 v[122:125], v[168:171], v[176:179], v[122:125]
	v_mfma_f32_16x16x32_bf16 v[118:121], v[148:151], v[184:187], v[118:121]
	v_mfma_f32_16x16x32_bf16 v[114:117], v[168:171], v[184:187], v[114:117]
	v_mfma_f32_16x16x32_bf16 v[102:105], v[148:151], v[192:195], v[102:105]
	v_mfma_f32_16x16x32_bf16 v[98:101], v[168:171], v[192:195], v[98:101]
	v_mfma_f32_16x16x32_bf16 v[86:89], v[148:151], v[224:227], v[86:89]
	v_mfma_f32_16x16x32_bf16 v[82:85], v[168:171], v[224:227], v[82:85]
	s_barrier
	s_add_i32 s50, 0, 0x1c000
	s_add_i32 s39, s39, s52
	s_mov_b32 m0, s39
	ds_read_b128 v[228:231], v141 offset:49152
	ds_read_b128 v[232:235], v141 offset:50176
	ds_read_b128 v[236:239], v141 offset:51200
	ds_read_b128 v[240:243], v141 offset:52224
	global_load_lds_dwordx4 v0, s[76:77]
	s_add_i32 m0, s39, 0x2000
	s_nop 0
	global_load_lds_dwordx4 v130, s[76:77]
	s_barrier
	s_waitcnt lgkmcnt(0)
	s_waitcnt lgkmcnt(0)
	v_mfma_f32_16x16x32_bf16 v[110:113], v[228:231], v[172:175], v[110:113]
	v_mfma_f32_16x16x32_bf16 v[106:109], v[236:239], v[172:175], v[106:109]
	v_mfma_f32_16x16x32_bf16 v[94:97], v[228:231], v[180:183], v[94:97]
	v_mfma_f32_16x16x32_bf16 v[90:93], v[236:239], v[180:183], v[90:93]
	v_mfma_f32_16x16x32_bf16 v[78:81], v[228:231], v[188:191], v[78:81]
	v_mfma_f32_16x16x32_bf16 v[74:77], v[236:239], v[188:191], v[74:77]
	v_mfma_f32_16x16x32_bf16 v[70:73], v[228:231], v[196:199], v[70:73]
	v_mfma_f32_16x16x32_bf16 v[66:69], v[236:239], v[196:199], v[66:69]
	v_mfma_f32_16x16x32_bf16 v[110:113], v[232:235], v[176:179], v[110:113]
	v_mfma_f32_16x16x32_bf16 v[106:109], v[240:243], v[176:179], v[106:109]
	v_mfma_f32_16x16x32_bf16 v[94:97], v[232:235], v[184:187], v[94:97]
	v_mfma_f32_16x16x32_bf16 v[90:93], v[240:243], v[184:187], v[90:93]
	v_mfma_f32_16x16x32_bf16 v[78:81], v[232:235], v[192:195], v[78:81]
	v_mfma_f32_16x16x32_bf16 v[74:77], v[240:243], v[192:195], v[74:77]
	v_mfma_f32_16x16x32_bf16 v[70:73], v[232:235], v[224:227], v[70:73]
	v_mfma_f32_16x16x32_bf16 v[66:69], v[240:243], v[224:227], v[66:69]
	s_mov_b32 m0, s57
	s_barrier
	ds_read_b128 v[172:175], v143 offset:49152
	ds_read_b128 v[176:179], v143 offset:50176
	ds_read_b128 v[180:183], v143 offset:51200
	ds_read_b128 v[184:187], v143 offset:52224
	ds_read_b128 v[188:191], v143 offset:53248
	ds_read_b128 v[192:195], v143 offset:54272
	ds_read_b128 v[196:199], v143 offset:55296
	ds_read_b128 v[224:227], v143 offset:56320
	global_load_lds_dwordx4 v134, s[78:79]
	s_mov_b32 m0, s58
	s_nop 0
	global_load_lds_dwordx4 v132, s[78:79]
	s_barrier
	s_waitcnt lgkmcnt(0)
	s_waitcnt lgkmcnt(0)
	v_mfma_f32_16x16x32_bf16 v[62:65], v[144:147], v[172:175], v[62:65]
	v_mfma_f32_16x16x32_bf16 v[58:61], v[152:155], v[172:175], v[58:61]
	v_mfma_f32_16x16x32_bf16 v[54:57], v[144:147], v[180:183], v[54:57]
	v_mfma_f32_16x16x32_bf16 v[50:53], v[152:155], v[180:183], v[50:53]
	v_mfma_f32_16x16x32_bf16 v[38:41], v[144:147], v[188:191], v[38:41]
	v_mfma_f32_16x16x32_bf16 v[34:37], v[152:155], v[188:191], v[34:37]
	v_mfma_f32_16x16x32_bf16 v[22:25], v[144:147], v[196:199], v[22:25]
	v_mfma_f32_16x16x32_bf16 v[18:21], v[152:155], v[196:199], v[18:21]
	v_mfma_f32_16x16x32_bf16 v[62:65], v[148:151], v[176:179], v[62:65]
	v_mfma_f32_16x16x32_bf16 v[58:61], v[168:171], v[176:179], v[58:61]
	v_mfma_f32_16x16x32_bf16 v[54:57], v[148:151], v[184:187], v[54:57]
	v_mfma_f32_16x16x32_bf16 v[50:53], v[168:171], v[184:187], v[50:53]
	v_mfma_f32_16x16x32_bf16 v[38:41], v[148:151], v[192:195], v[38:41]
	v_mfma_f32_16x16x32_bf16 v[34:37], v[168:171], v[192:195], v[34:37]
	v_mfma_f32_16x16x32_bf16 v[22:25], v[148:151], v[224:227], v[22:25]
	v_mfma_f32_16x16x32_bf16 v[18:21], v[168:171], v[224:227], v[18:21]
	s_barrier
	s_add_u32 s48, s48, 0x80080
	s_addc_u32 s49, s49, 0
	s_add_i32 s39, s50, s52
	s_mov_b32 m0, s39
	s_nop 0
	global_load_lds_dwordx4 v0, s[48:49]
	s_add_i32 m0, s39, 0x2000
	s_nop 0
	global_load_lds_dwordx4 v130, s[48:49]
	s_waitcnt vmcnt(6)
	s_barrier
	v_mfma_f32_16x16x32_bf16 v[46:49], v[228:231], v[172:175], v[46:49]
	v_mfma_f32_16x16x32_bf16 v[42:45], v[236:239], v[172:175], v[42:45]
	v_mfma_f32_16x16x32_bf16 v[30:33], v[228:231], v[180:183], v[30:33]
	v_mfma_f32_16x16x32_bf16 v[26:29], v[236:239], v[180:183], v[26:29]
	v_mfma_f32_16x16x32_bf16 v[14:17], v[228:231], v[188:191], v[14:17]
	v_mfma_f32_16x16x32_bf16 v[10:13], v[236:239], v[188:191], v[10:13]
	v_mfma_f32_16x16x32_bf16 v[6:9], v[228:231], v[196:199], v[6:9]
	v_mfma_f32_16x16x32_bf16 v[2:5], v[236:239], v[196:199], v[2:5]
	v_mfma_f32_16x16x32_bf16 v[46:49], v[232:235], v[176:179], v[46:49]
	v_mfma_f32_16x16x32_bf16 v[42:45], v[240:243], v[176:179], v[42:45]
	v_mfma_f32_16x16x32_bf16 v[30:33], v[232:235], v[184:187], v[30:33]
	v_mfma_f32_16x16x32_bf16 v[26:29], v[240:243], v[184:187], v[26:29]
	v_mfma_f32_16x16x32_bf16 v[14:17], v[232:235], v[192:195], v[14:17]
	v_mfma_f32_16x16x32_bf16 v[10:13], v[240:243], v[192:195], v[10:13]
	v_mfma_f32_16x16x32_bf16 v[6:9], v[232:235], v[224:227], v[6:9]
	v_mfma_f32_16x16x32_bf16 v[2:5], v[240:243], v[224:227], v[2:5]
	s_add_i32 s13, s13, 2
	s_add_u32 s46, s46, 0x100
	s_addc_u32 s47, s47, 0
	s_add_u32 s1, s1, 0x100
	s_addc_u32 s12, s12, 0
	s_cmp_gt_u32 s13, 29
	s_barrier
	s_cbranch_scc0 .LBB0_234
	v_readlane_b32 s6, v255, 23
	v_lshl_add_u32 v150, s61, 8, v140
	v_lshl_or_b32 v144, s60, 8, v142
	v_readlane_b32 s7, v255, 24
	v_ashrrev_i32_e32 v145, 31, v144
	s_movk_i32 s1, 0x5800
	v_mov_b64_e32 v[146:147], s[6:7]
	v_cvt_pk_bf16_f32 v70, v70, v71
	v_cvt_pk_bf16_f32 v71, v72, v73
	v_cvt_pk_bf16_f32 v72, v66, v67
	v_add_u32_e32 v66, 0x80, v150
	v_mad_i64_i32 v[148:149], s[12:13], v150, s1, v[146:147]
	v_lshlrev_b64 v[144:145], 1, v[144:145]
	v_cvt_pk_bf16_f32 v110, v110, v111
	v_cvt_pk_bf16_f32 v111, v112, v113
	v_cvt_pk_bf16_f32 v112, v106, v107
	v_or_b32_e32 v106, 16, v150
	v_mad_i64_i32 v[66:67], s[12:13], v66, s1, v[146:147]
	v_cvt_pk_bf16_f32 v46, v46, v47
	v_cvt_pk_bf16_f32 v47, v48, v49
	v_cvt_pk_bf16_f32 v48, v42, v43
	v_add_u32_e32 v42, 0x90, v150
	v_lshl_add_u64 v[148:149], v[148:149], 0, v[144:145]
	v_cvt_pk_bf16_f32 v113, v108, v109
	v_mad_i64_i32 v[106:107], s[12:13], v106, s1, v[146:147]
	v_cvt_pk_bf16_f32 v94, v94, v95
	v_cvt_pk_bf16_f32 v95, v96, v97
	v_cvt_pk_bf16_f32 v96, v90, v91
	v_or_b32_e32 v90, 32, v150
	v_lshl_add_u64 v[66:67], v[66:67], 0, v[144:145]
	v_cvt_pk_bf16_f32 v49, v44, v45
	v_mad_i64_i32 v[42:43], s[12:13], v42, s1, v[146:147]
	v_cvt_pk_bf16_f32 v30, v30, v31
	v_cvt_pk_bf16_f32 v31, v32, v33
	v_cvt_pk_bf16_f32 v32, v26, v27
	v_add_u32_e32 v26, 0xa0, v150
	global_store_dwordx4 v[148:149], v[110:113], off offset:256
	v_cvt_pk_bf16_f32 v97, v92, v93
	v_mad_i64_i32 v[90:91], s[12:13], v90, s1, v[146:147]
	v_lshl_add_u64 v[110:111], v[106:107], 0, v[144:145]
	v_cvt_pk_bf16_f32 v78, v78, v79
	v_cvt_pk_bf16_f32 v79, v80, v81
	v_cvt_pk_bf16_f32 v80, v74, v75
	v_or_b32_e32 v74, 48, v150
	global_store_dwordx4 v[66:67], v[46:49], off offset:256
	v_cvt_pk_bf16_f32 v33, v28, v29
	v_mad_i64_i32 v[26:27], s[12:13], v26, s1, v[146:147]
	v_lshl_add_u64 v[46:47], v[42:43], 0, v[144:145]
	v_cvt_pk_bf16_f32 v14, v14, v15
	v_cvt_pk_bf16_f32 v15, v16, v17
	v_cvt_pk_bf16_f32 v16, v10, v11
	v_add_u32_e32 v10, 0xb0, v150
	global_store_dwordx4 v[110:111], v[94:97], off offset:256
	v_cvt_pk_bf16_f32 v81, v76, v77
	v_mad_i64_i32 v[74:75], s[12:13], v74, s1, v[146:147]
	v_lshl_add_u64 v[94:95], v[90:91], 0, v[144:145]
	global_store_dwordx4 v[46:47], v[30:33], off offset:256
	v_cvt_pk_bf16_f32 v17, v12, v13
	v_mad_i64_i32 v[10:11], s[12:13], v10, s1, v[146:147]
	v_lshl_add_u64 v[30:31], v[26:27], 0, v[144:145]
	v_cvt_pk_bf16_f32 v126, v126, v127
	v_cvt_pk_bf16_f32 v127, v128, v129
	v_cvt_pk_bf16_f32 v128, v122, v123
	v_cvt_pk_bf16_f32 v129, v124, v125
	v_cvt_pk_bf16_f32 v106, v118, v119
	v_cvt_pk_bf16_f32 v107, v120, v121
	v_cvt_pk_bf16_f32 v108, v114, v115
	v_cvt_pk_bf16_f32 v109, v116, v117
	v_cvt_pk_bf16_f32 v90, v102, v103
	v_cvt_pk_bf16_f32 v91, v104, v105
	v_cvt_pk_bf16_f32 v92, v98, v99
	v_cvt_pk_bf16_f32 v93, v100, v101
	global_store_dwordx4 v[94:95], v[78:81], off offset:256
	v_cvt_pk_bf16_f32 v76, v82, v83
	v_cvt_pk_bf16_f32 v77, v84, v85
	v_lshl_add_u64 v[78:79], v[74:75], 0, v[144:145]
	v_cvt_pk_bf16_f32 v74, v86, v87
	v_cvt_pk_bf16_f32 v75, v88, v89
	v_cvt_pk_bf16_f32 v73, v68, v69
	v_cvt_pk_bf16_f32 v62, v62, v63
	v_cvt_pk_bf16_f32 v63, v64, v65
	v_cvt_pk_bf16_f32 v64, v58, v59
	v_cvt_pk_bf16_f32 v65, v60, v61
	v_cvt_pk_bf16_f32 v42, v54, v55
	v_cvt_pk_bf16_f32 v43, v56, v57
	v_cvt_pk_bf16_f32 v44, v50, v51
	v_cvt_pk_bf16_f32 v45, v52, v53
	v_cvt_pk_bf16_f32 v26, v38, v39
	v_cvt_pk_bf16_f32 v27, v40, v41
	v_cvt_pk_bf16_f32 v28, v34, v35
	v_cvt_pk_bf16_f32 v29, v36, v37
	global_store_dwordx4 v[30:31], v[14:17], off offset:256
	v_cvt_pk_bf16_f32 v12, v18, v19
	v_cvt_pk_bf16_f32 v13, v20, v21
	v_lshl_add_u64 v[14:15], v[10:11], 0, v[144:145]
	v_cvt_pk_bf16_f32 v10, v22, v23
	v_cvt_pk_bf16_f32 v11, v24, v25
	v_cvt_pk_bf16_f32 v6, v6, v7
	v_cvt_pk_bf16_f32 v7, v8, v9
	v_cvt_pk_bf16_f32 v8, v2, v3
	v_cvt_pk_bf16_f32 v9, v4, v5
	s_and_b64 vcc, exec, s[40:41]
	s_mov_b32 s60, s0
	s_mov_b32 s61, s38
	s_mov_b64 s[48:49], s[44:45]
	s_mov_b64 s[46:47], s[42:43]
	global_store_dwordx4 v[148:149], v[126:129], off
	global_store_dwordx4 v[110:111], v[106:109], off
	global_store_dwordx4 v[94:95], v[90:93], off
	global_store_dwordx4 v[78:79], v[74:77], off
	global_store_dwordx4 v[78:79], v[70:73], off offset:256
	global_store_dwordx4 v[66:67], v[62:65], off
	global_store_dwordx4 v[46:47], v[42:45], off
	global_store_dwordx4 v[30:31], v[26:29], off
	global_store_dwordx4 v[14:15], v[10:13], off
	global_store_dwordx4 v[14:15], v[6:9], off offset:256
	s_cbranch_vccz .LBB0_227
	s_waitcnt vmcnt(0)
	v_readlane_b32 s60, v255, 21
	s_cmpk_gt_u32 s36, 0xff
	s_mov_b32 s18, s60
	v_readlane_b32 s61, v255, 22
	s_cbranch_scc1 .LBB0_238
	s_barrier

.LBB0_267:
	v_readlane_b32 s50, v253, 8
	v_readlane_b32 s51, v253, 9
	v_mov_b32_e32 v131, v1
	v_readlane_b32 s12, v253, 4
	v_lshl_add_u64 v[8:9], s[50:51], 0, v[0:1]
	v_lshl_add_u64 v[10:11], s[50:51], 0, v[130:131]
	v_readlane_b32 s13, v253, 5
	s_add_i32 m0, s55, 0x18000
	v_lshl_add_u64 v[8:9], v[8:9], 0, s[94:95]
	v_lshl_add_u64 v[12:13], s[12:13], 0, v[0:1]
	s_waitcnt vmcnt(4)
	s_barrier
	global_load_lds_dwordx4 v[8:9], off
	v_lshl_add_u64 v[8:9], v[10:11], 0, s[94:95]
	s_add_i32 m0, s55, 0x1a000
	s_add_i32 s59, s55, 0x8000
	v_lshl_add_u64 v[14:15], s[12:13], 0, v[130:131]
	global_load_lds_dwordx4 v[8:9], off
	v_lshl_add_u64 v[8:9], v[12:13], 0, s[94:95]
	s_mov_b32 m0, s59
	s_add_i32 s60, s55, 0xa000
	v_readlane_b32 s38, v253, 10
	global_load_lds_dwordx4 v[8:9], off
	v_lshl_add_u64 v[8:9], v[14:15], 0, s[94:95]
	s_mov_b32 m0, s60
	v_readlane_b32 s39, v253, 11
	global_load_lds_dwordx4 v[8:9], off
	s_add_i32 m0, s55, 0x1c000
	v_lshl_add_u64 v[8:9], s[38:39], 0, v[0:1]
	global_load_lds_dwordx4 v[8:9], off
	v_lshl_add_u64 v[8:9], s[38:39], 0, v[130:131]
	s_add_i32 m0, s55, 0x1e000
	v_bfe_u32 v17, v166, 4, 2
	global_load_lds_dwordx4 v[8:9], off
	v_lshlrev_b32_e32 v8, 15, v5
	v_and_b32_e32 v8, 0xffff0000, v8
	v_lshl_add_u32 v6, v6, 12, v8
	v_and_b32_e32 v5, 1, v5
	v_lshl_or_b32 v5, v5, 6, v6
	v_and_b32_e32 v16, 15, v166
	v_lshlrev_b32_e32 v18, 4, v17
	v_lshl_add_u32 v132, v7, 1, v5
	v_lshlrev_b32_e32 v5, 15, v2
	v_lshl_or_b32 v152, s1, 6, v16
	v_lshl_or_b32 v16, v16, 6, v18
	v_lshlrev_b32_e32 v18, 2, v166
	s_lshl_b32 s0, s0, 5
	v_and_b32_e32 v5, 0xffff0000, v5
	s_lshl_b32 s1, s1, 13
	v_and_b32_e32 v18, 32, v18
	s_and_b32 s0, s0, 0x60
	s_waitcnt vmcnt(6)
	v_lshl_add_u32 v3, v3, 12, v5
	v_and_b32_e32 v2, 1, v2
	v_bitop3_b32 v19, v16, s1, v18 bitop3:0xde
	s_lshl_b32 s1, s0, 7
	v_lshl_or_b32 v154, v17, 2, s0
	v_lshl_or_b32 v2, v2, 6, v3
	v_readlane_b32 s0, v250, 8
	v_bitop3_b32 v153, s1, v16, v18 bitop3:0xf6
	v_add_u32_e32 v153, 0x10000, v153
	v_mov_b32_e32 v133, v1
	v_lshl_add_u32 v134, v4, 1, v2
	v_mov_b32_e32 v135, v1
	s_mov_b32 s61, 0
	v_add_u32_e32 v155, 0, v19
	v_readlane_b32 s41, v252, 55
	v_readlane_b32 s64, v252, 51
	v_readlane_b32 s65, v252, 52
	v_readlane_b32 s63, v252, 54
	s_mov_b32 s40, s0
	s_mov_b64 s[0:1], s[12:13]
	s_barrier
	s_branch .LBB0_270

.LBB0_282:
	s_add_i32 s67, s50, 2
	s_add_u32 s51, s0, 0xfff80080
	s_addc_u32 s52, s1, -1
	s_add_i32 s68, 0, 0x10000
	ds_read_b128 v[136:139], v153
	ds_read_b128 v[140:143], v153 offset:1024
	ds_read_b128 v[144:147], v153 offset:2048
	ds_read_b128 v[148:151], v153 offset:3072
	s_cmp_eq_u32 s12, s50
	s_cselect_b32 s50, s48, s13
	s_cselect_b32 s53, s47, s52
	s_cselect_b32 s52, s46, s51
	s_cselect_b32 s51, s49, s66
	s_add_i32 m0, s55, 0xc000
	ds_read_b128 v[168:171], v155
	ds_read_b128 v[172:175], v155 offset:1024
	ds_read_b128 v[176:179], v155 offset:2048
	ds_read_b128 v[180:183], v155 offset:3072
	ds_read_b128 v[184:187], v155 offset:4096
	ds_read_b128 v[188:191], v155 offset:5120
	ds_read_b128 v[192:195], v155 offset:6144
	ds_read_b128 v[196:199], v155 offset:7168
	global_load_lds_dwordx4 v132, s[0:1]
	s_add_i32 m0, s55, 0xe000
	s_nop 0
	global_load_lds_dwordx4 v134, s[0:1]
	s_waitcnt lgkmcnt(8)
	s_barrier
	s_waitcnt lgkmcnt(0)
	s_waitcnt lgkmcnt(0)
	v_mfma_f32_16x16x32_bf16 v[126:129], v[136:139], v[168:171], v[126:129]
	v_mfma_f32_16x16x32_bf16 v[122:125], v[144:147], v[168:171], v[122:125]
	v_mfma_f32_16x16x32_bf16 v[110:113], v[136:139], v[176:179], v[110:113]
	v_mfma_f32_16x16x32_bf16 v[106:109], v[144:147], v[176:179], v[106:109]
	v_mfma_f32_16x16x32_bf16 v[94:97], v[136:139], v[184:187], v[94:97]
	v_mfma_f32_16x16x32_bf16 v[90:93], v[144:147], v[184:187], v[90:93]
	v_mfma_f32_16x16x32_bf16 v[78:81], v[136:139], v[192:195], v[78:81]
	v_mfma_f32_16x16x32_bf16 v[74:77], v[144:147], v[192:195], v[74:77]
	v_mfma_f32_16x16x32_bf16 v[126:129], v[140:143], v[172:175], v[126:129]
	v_mfma_f32_16x16x32_bf16 v[122:125], v[148:151], v[172:175], v[122:125]
	v_mfma_f32_16x16x32_bf16 v[110:113], v[140:143], v[180:183], v[110:113]
	v_mfma_f32_16x16x32_bf16 v[106:109], v[148:151], v[180:183], v[106:109]
	v_mfma_f32_16x16x32_bf16 v[94:97], v[140:143], v[188:191], v[94:97]
	v_mfma_f32_16x16x32_bf16 v[90:93], v[148:151], v[188:191], v[90:93]
	v_mfma_f32_16x16x32_bf16 v[78:81], v[140:143], v[196:199], v[78:81]
	v_mfma_f32_16x16x32_bf16 v[74:77], v[148:151], v[196:199], v[74:77]
	s_barrier
	s_add_i32 s70, 0, 0x14000
	s_add_i32 s68, s68, s54
	ds_read_b128 v[224:227], v153 offset:16384
	ds_read_b128 v[228:231], v153 offset:17408
	ds_read_b128 v[232:235], v153 offset:18432
	ds_read_b128 v[236:239], v153 offset:19456
	s_add_u32 s76, s50, s94
	s_addc_u32 s77, s51, s95
	s_mov_b32 m0, s68
	s_nop 0
	global_load_lds_dwordx4 v0, s[50:51]
	s_add_i32 m0, s68, 0x2000
	s_nop 0
	global_load_lds_dwordx4 v130, s[50:51]
	s_barrier
	s_waitcnt lgkmcnt(0)
	s_waitcnt lgkmcnt(0)
	v_mfma_f32_16x16x32_bf16 v[118:121], v[224:227], v[168:171], v[118:121]
	v_mfma_f32_16x16x32_bf16 v[114:117], v[232:235], v[168:171], v[114:117]
	v_mfma_f32_16x16x32_bf16 v[102:105], v[224:227], v[176:179], v[102:105]
	v_mfma_f32_16x16x32_bf16 v[98:101], v[232:235], v[176:179], v[98:101]
	v_mfma_f32_16x16x32_bf16 v[86:89], v[224:227], v[184:187], v[86:89]
	v_mfma_f32_16x16x32_bf16 v[82:85], v[232:235], v[184:187], v[82:85]
	v_mfma_f32_16x16x32_bf16 v[70:73], v[224:227], v[192:195], v[70:73]
	v_mfma_f32_16x16x32_bf16 v[66:69], v[232:235], v[192:195], v[66:69]
	v_mfma_f32_16x16x32_bf16 v[118:121], v[228:231], v[172:175], v[118:121]
	v_mfma_f32_16x16x32_bf16 v[114:117], v[236:239], v[172:175], v[114:117]
	v_mfma_f32_16x16x32_bf16 v[102:105], v[228:231], v[180:183], v[102:105]
	v_mfma_f32_16x16x32_bf16 v[98:101], v[236:239], v[180:183], v[98:101]
	v_mfma_f32_16x16x32_bf16 v[86:89], v[228:231], v[188:191], v[86:89]
	v_mfma_f32_16x16x32_bf16 v[82:85], v[236:239], v[188:191], v[82:85]
	v_mfma_f32_16x16x32_bf16 v[70:73], v[228:231], v[196:199], v[70:73]
	v_mfma_f32_16x16x32_bf16 v[66:69], v[236:239], v[196:199], v[66:69]
	s_mov_b32 m0, s55
	s_add_u32 s78, s52, s94
	s_addc_u32 s79, s53, s95
	s_barrier
	ds_read_b128 v[168:171], v155 offset:16384
	ds_read_b128 v[172:175], v155 offset:17408
	ds_read_b128 v[176:179], v155 offset:18432
	ds_read_b128 v[180:183], v155 offset:19456
	ds_read_b128 v[184:187], v155 offset:20480
	ds_read_b128 v[188:191], v155 offset:21504
	ds_read_b128 v[192:195], v155 offset:22528
	ds_read_b128 v[196:199], v155 offset:23552
	global_load_lds_dwordx4 v0, s[52:53]
	s_mov_b32 m0, s56
	s_nop 0
	global_load_lds_dwordx4 v130, s[52:53]
	s_barrier
	s_waitcnt lgkmcnt(0)
	s_waitcnt lgkmcnt(0)
	v_mfma_f32_16x16x32_bf16 v[62:65], v[136:139], v[168:171], v[62:65]
	v_mfma_f32_16x16x32_bf16 v[58:61], v[144:147], v[168:171], v[58:61]
	v_mfma_f32_16x16x32_bf16 v[46:49], v[136:139], v[176:179], v[46:49]
	v_mfma_f32_16x16x32_bf16 v[42:45], v[144:147], v[176:179], v[42:45]
	v_mfma_f32_16x16x32_bf16 v[30:33], v[136:139], v[184:187], v[30:33]
	v_mfma_f32_16x16x32_bf16 v[26:29], v[144:147], v[184:187], v[26:29]
	v_mfma_f32_16x16x32_bf16 v[14:17], v[136:139], v[192:195], v[14:17]
	v_mfma_f32_16x16x32_bf16 v[10:13], v[144:147], v[192:195], v[10:13]
	v_mfma_f32_16x16x32_bf16 v[62:65], v[140:143], v[172:175], v[62:65]
	v_mfma_f32_16x16x32_bf16 v[58:61], v[148:151], v[172:175], v[58:61]
	v_mfma_f32_16x16x32_bf16 v[46:49], v[140:143], v[180:183], v[46:49]
	v_mfma_f32_16x16x32_bf16 v[42:45], v[148:151], v[180:183], v[42:45]
	v_mfma_f32_16x16x32_bf16 v[30:33], v[140:143], v[188:191], v[30:33]
	v_mfma_f32_16x16x32_bf16 v[26:29], v[148:151], v[188:191], v[26:29]
	v_mfma_f32_16x16x32_bf16 v[14:17], v[140:143], v[196:199], v[14:17]
	v_mfma_f32_16x16x32_bf16 v[10:13], v[148:151], v[196:199], v[10:13]
	s_barrier
	s_add_u32 s68, s50, 0x80000
	s_addc_u32 s69, s51, 0
	s_add_i32 s70, s70, s54
	s_mov_b32 m0, s70
	s_nop 0
	global_load_lds_dwordx4 v0, s[68:69]
	s_add_i32 m0, s70, 0x2000
	s_nop 0
	global_load_lds_dwordx4 v130, s[68:69]
	s_waitcnt vmcnt(6)
	s_barrier
	v_mfma_f32_16x16x32_bf16 v[54:57], v[224:227], v[168:171], v[54:57]
	v_mfma_f32_16x16x32_bf16 v[50:53], v[232:235], v[168:171], v[50:53]
	v_mfma_f32_16x16x32_bf16 v[38:41], v[224:227], v[176:179], v[38:41]
	v_mfma_f32_16x16x32_bf16 v[34:37], v[232:235], v[176:179], v[34:37]
	v_mfma_f32_16x16x32_bf16 v[22:25], v[224:227], v[184:187], v[22:25]
	v_mfma_f32_16x16x32_bf16 v[18:21], v[232:235], v[184:187], v[18:21]
	v_mfma_f32_16x16x32_bf16 v[6:9], v[224:227], v[192:195], v[6:9]
	v_mfma_f32_16x16x32_bf16 v[2:5], v[232:235], v[192:195], v[2:5]
	v_mfma_f32_16x16x32_bf16 v[54:57], v[228:231], v[172:175], v[54:57]
	v_mfma_f32_16x16x32_bf16 v[50:53], v[236:239], v[172:175], v[50:53]
	v_mfma_f32_16x16x32_bf16 v[38:41], v[228:231], v[180:183], v[38:41]
	v_mfma_f32_16x16x32_bf16 v[34:37], v[236:239], v[180:183], v[34:37]
	v_mfma_f32_16x16x32_bf16 v[22:25], v[228:231], v[188:191], v[22:25]
	v_mfma_f32_16x16x32_bf16 v[18:21], v[236:239], v[188:191], v[18:21]
	v_mfma_f32_16x16x32_bf16 v[6:9], v[228:231], v[196:199], v[6:9]
	v_mfma_f32_16x16x32_bf16 v[2:5], v[236:239], v[196:199], v[2:5]
	s_add_i32 s68, 0, 0x18000
	s_barrier
	ds_read_b128 v[136:139], v153 offset:32768
	ds_read_b128 v[140:143], v153 offset:33792
	ds_read_b128 v[144:147], v153 offset:34816
	ds_read_b128 v[148:151], v153 offset:35840
	s_add_u32 s52, s52, 0x80000
	s_addc_u32 s53, s53, 0
	s_mov_b32 m0, s57
	ds_read_b128 v[168:171], v155 offset:32768
	ds_read_b128 v[172:175], v155 offset:33792
	ds_read_b128 v[176:179], v155 offset:34816
	ds_read_b128 v[180:183], v155 offset:35840
	ds_read_b128 v[184:187], v155 offset:36864
	ds_read_b128 v[188:191], v155 offset:37888
	ds_read_b128 v[192:195], v155 offset:38912
	ds_read_b128 v[196:199], v155 offset:39936
	global_load_lds_dwordx4 v0, s[52:53]
	s_mov_b32 m0, s58
	s_nop 0
	global_load_lds_dwordx4 v130, s[52:53]
	s_waitcnt lgkmcnt(8)
	s_barrier
	s_waitcnt lgkmcnt(0)
	s_waitcnt lgkmcnt(0)
	v_mfma_f32_16x16x32_bf16 v[126:129], v[136:139], v[168:171], v[126:129]
	v_mfma_f32_16x16x32_bf16 v[122:125], v[144:147], v[168:171], v[122:125]
	v_mfma_f32_16x16x32_bf16 v[110:113], v[136:139], v[176:179], v[110:113]
	v_mfma_f32_16x16x32_bf16 v[106:109], v[144:147], v[176:179], v[106:109]
	v_mfma_f32_16x16x32_bf16 v[94:97], v[136:139], v[184:187], v[94:97]
	v_mfma_f32_16x16x32_bf16 v[90:93], v[144:147], v[184:187], v[90:93]
	v_mfma_f32_16x16x32_bf16 v[78:81], v[136:139], v[192:195], v[78:81]
	v_mfma_f32_16x16x32_bf16 v[74:77], v[144:147], v[192:195], v[74:77]
	v_mfma_f32_16x16x32_bf16 v[126:129], v[140:143], v[172:175], v[126:129]
	v_mfma_f32_16x16x32_bf16 v[122:125], v[148:151], v[172:175], v[122:125]
	v_mfma_f32_16x16x32_bf16 v[110:113], v[140:143], v[180:183], v[110:113]
	v_mfma_f32_16x16x32_bf16 v[106:109], v[148:151], v[180:183], v[106:109]
	v_mfma_f32_16x16x32_bf16 v[94:97], v[140:143], v[188:191], v[94:97]
	v_mfma_f32_16x16x32_bf16 v[90:93], v[148:151], v[188:191], v[90:93]
	v_mfma_f32_16x16x32_bf16 v[78:81], v[140:143], v[196:199], v[78:81]
	v_mfma_f32_16x16x32_bf16 v[74:77], v[148:151], v[196:199], v[74:77]
	s_barrier
	s_add_i32 s52, 0, 0x1c000
	s_add_i32 s53, s68, s54
	s_mov_b32 m0, s53
	ds_read_b128 v[224:227], v153 offset:49152
	ds_read_b128 v[228:231], v153 offset:50176
	ds_read_b128 v[232:235], v153 offset:51200
	ds_read_b128 v[236:239], v153 offset:52224
	global_load_lds_dwordx4 v0, s[76:77]
	s_add_i32 m0, s53, 0x2000
	s_nop 0
	global_load_lds_dwordx4 v130, s[76:77]
	s_barrier
	s_waitcnt lgkmcnt(0)
	s_waitcnt lgkmcnt(0)
	v_mfma_f32_16x16x32_bf16 v[118:121], v[224:227], v[168:171], v[118:121]
	v_mfma_f32_16x16x32_bf16 v[114:117], v[232:235], v[168:171], v[114:117]
	v_mfma_f32_16x16x32_bf16 v[102:105], v[224:227], v[176:179], v[102:105]
	v_mfma_f32_16x16x32_bf16 v[98:101], v[232:235], v[176:179], v[98:101]
	v_mfma_f32_16x16x32_bf16 v[86:89], v[224:227], v[184:187], v[86:89]
	v_mfma_f32_16x16x32_bf16 v[82:85], v[232:235], v[184:187], v[82:85]
	v_mfma_f32_16x16x32_bf16 v[70:73], v[224:227], v[192:195], v[70:73]
	v_mfma_f32_16x16x32_bf16 v[66:69], v[232:235], v[192:195], v[66:69]
	v_mfma_f32_16x16x32_bf16 v[118:121], v[228:231], v[172:175], v[118:121]
	v_mfma_f32_16x16x32_bf16 v[114:117], v[236:239], v[172:175], v[114:117]
	v_mfma_f32_16x16x32_bf16 v[102:105], v[228:231], v[180:183], v[102:105]
	v_mfma_f32_16x16x32_bf16 v[98:101], v[236:239], v[180:183], v[98:101]
	v_mfma_f32_16x16x32_bf16 v[86:89], v[228:231], v[188:191], v[86:89]
	v_mfma_f32_16x16x32_bf16 v[82:85], v[236:239], v[188:191], v[82:85]
	v_mfma_f32_16x16x32_bf16 v[70:73], v[228:231], v[196:199], v[70:73]
	v_mfma_f32_16x16x32_bf16 v[66:69], v[236:239], v[196:199], v[66:69]
	s_mov_b32 m0, s59
	s_barrier
	ds_read_b128 v[168:171], v155 offset:49152
	ds_read_b128 v[172:175], v155 offset:50176
	ds_read_b128 v[176:179], v155 offset:51200
	ds_read_b128 v[180:183], v155 offset:52224
	ds_read_b128 v[184:187], v155 offset:53248
	ds_read_b128 v[188:191], v155 offset:54272
	ds_read_b128 v[192:195], v155 offset:55296
	ds_read_b128 v[196:199], v155 offset:56320
	global_load_lds_dwordx4 v0, s[78:79]
	s_mov_b32 m0, s60
	s_nop 0
	global_load_lds_dwordx4 v130, s[78:79]
	s_barrier
	s_waitcnt lgkmcnt(0)
	s_waitcnt lgkmcnt(0)
	v_mfma_f32_16x16x32_bf16 v[62:65], v[136:139], v[168:171], v[62:65]
	v_mfma_f32_16x16x32_bf16 v[58:61], v[144:147], v[168:171], v[58:61]
	v_mfma_f32_16x16x32_bf16 v[46:49], v[136:139], v[176:179], v[46:49]
	v_mfma_f32_16x16x32_bf16 v[42:45], v[144:147], v[176:179], v[42:45]
	v_mfma_f32_16x16x32_bf16 v[30:33], v[136:139], v[184:187], v[30:33]
	v_mfma_f32_16x16x32_bf16 v[26:29], v[144:147], v[184:187], v[26:29]
	v_mfma_f32_16x16x32_bf16 v[14:17], v[136:139], v[192:195], v[14:17]
	v_mfma_f32_16x16x32_bf16 v[10:13], v[144:147], v[192:195], v[10:13]
	v_mfma_f32_16x16x32_bf16 v[62:65], v[140:143], v[172:175], v[62:65]
	v_mfma_f32_16x16x32_bf16 v[58:61], v[148:151], v[172:175], v[58:61]
	v_mfma_f32_16x16x32_bf16 v[46:49], v[140:143], v[180:183], v[46:49]
	v_mfma_f32_16x16x32_bf16 v[42:45], v[148:151], v[180:183], v[42:45]
	v_mfma_f32_16x16x32_bf16 v[30:33], v[140:143], v[188:191], v[30:33]
	v_mfma_f32_16x16x32_bf16 v[26:29], v[148:151], v[188:191], v[26:29]
	v_mfma_f32_16x16x32_bf16 v[14:17], v[140:143], v[196:199], v[14:17]
	v_mfma_f32_16x16x32_bf16 v[10:13], v[148:151], v[196:199], v[10:13]
	s_barrier
	s_add_u32 s50, s50, 0x80080
	s_addc_u32 s51, s51, 0
	s_add_i32 s52, s52, s54
	s_mov_b32 m0, s52
	s_nop 0
	global_load_lds_dwordx4 v0, s[50:51]
	s_add_i32 m0, s52, 0x2000
	s_nop 0
	global_load_lds_dwordx4 v130, s[50:51]
	s_waitcnt vmcnt(6)
	s_barrier
	v_mfma_f32_16x16x32_bf16 v[54:57], v[224:227], v[168:171], v[54:57]
	v_mfma_f32_16x16x32_bf16 v[50:53], v[232:235], v[168:171], v[50:53]
	v_mfma_f32_16x16x32_bf16 v[38:41], v[224:227], v[176:179], v[38:41]
	v_mfma_f32_16x16x32_bf16 v[34:37], v[232:235], v[176:179], v[34:37]
	v_mfma_f32_16x16x32_bf16 v[22:25], v[224:227], v[184:187], v[22:25]
	v_mfma_f32_16x16x32_bf16 v[18:21], v[232:235], v[184:187], v[18:21]
	v_mfma_f32_16x16x32_bf16 v[6:9], v[224:227], v[192:195], v[6:9]
	v_mfma_f32_16x16x32_bf16 v[2:5], v[232:235], v[192:195], v[2:5]
	v_mfma_f32_16x16x32_bf16 v[54:57], v[228:231], v[172:175], v[54:57]
	v_mfma_f32_16x16x32_bf16 v[50:53], v[236:239], v[172:175], v[50:53]
	v_mfma_f32_16x16x32_bf16 v[38:41], v[228:231], v[180:183], v[38:41]
	v_mfma_f32_16x16x32_bf16 v[34:37], v[236:239], v[180:183], v[34:37]
	v_mfma_f32_16x16x32_bf16 v[22:25], v[228:231], v[188:191], v[22:25]
	v_mfma_f32_16x16x32_bf16 v[18:21], v[236:239], v[188:191], v[18:21]
	v_mfma_f32_16x16x32_bf16 v[6:9], v[228:231], v[196:199], v[6:9]
	v_mfma_f32_16x16x32_bf16 v[2:5], v[236:239], v[196:199], v[2:5]
	s_add_u32 s0, s0, 0x100
	s_addc_u32 s1, s1, 0
	s_add_u32 s13, s13, 0x100
	s_addc_u32 s66, s66, 0
	s_cmp_ge_i32 s67, s41
	s_mov_b32 s50, s67
	s_barrier
	s_cbranch_scc0 .LBB0_282
	s_cmp_eq_u32 s63, 2
	s_cbranch_scc1 .Lepi6_orig
	v_readlane_b32 s90, v255, 17
	v_readlane_b32 s91, v255, 18
	v_readlane_b32 s96, v255, 19
	v_readlane_b32 s97, v255, 20
	v_readlane_b32 s8, v255, 25
	v_readlane_b32 s9, v255, 26
	v_readlane_b32 s68, v253, 58
	v_readlane_b32 s69, v253, 59
	v_lshl_or_b32 v156, s64, 8, v154
	v_lshlrev_b32_e32 v156, 2, v156
	v_lshl_add_u32 v157, v152, 13, v156
	s_lshl_b32 s72, s65, 21
	s_add_u32 s74, s68, s72
	s_addc_u32 s75, s69, 0
	s_add_u32 s76, s22, s72
	s_addc_u32 s77, s23, 0
	s_lshr_b32 s73, s65, 3
	s_mul_i32 s73, s73, 0xc000
	s_add_u32 s73, s73, 0x4000
	s_add_u32 s70, s90, s73
	s_addc_u32 s71, s91, 0
	global_load_dwordx4 v[140:143], v156, s[70:71]
	global_load_dwordx4 v[144:147], v156, s[70:71] offset:64
	global_load_dwordx4 v[148:151], v156, s[70:71] offset:512
	global_load_dwordx4 v[168:171], v156, s[70:71] offset:576
	global_load_dwordx4 v[224:227], v157, s[74:75] nt
	global_load_dwordx4 v[228:231], v157, s[74:75] offset:64 nt
	global_load_dwordx4 v[232:235], v157, s[74:75] offset:512 nt
	global_load_dwordx4 v[236:239], v157, s[74:75] offset:576 nt
	s_add_u32 s74, s74, 0x20000
	s_addc_u32 s75, s75, 0
	global_load_dwordx4 v[240:243], v157, s[74:75] nt
	global_load_dwordx4 v[244:247], v157, s[74:75] offset:64 nt
	s_waitcnt vmcnt(5)
	v_pk_fma_f32 v[128:129], v[128:129], v[142:143], v[226:227]
	v_pk_fma_f32 v[126:127], v[126:127], v[140:141], v[224:225]
	global_store_dwordx4 v157, v[126:129], s[76:77]
	global_load_dwordx4 v[224:227], v157, s[74:75] offset:512 nt
	s_waitcnt vmcnt(6)
	v_pk_fma_f32 v[124:125], v[124:125], v[146:147], v[230:231]
	v_pk_fma_f32 v[122:123], v[122:123], v[144:145], v[228:229]
	global_store_dwordx4 v157, v[122:125], s[76:77] offset:64
	global_load_dwordx4 v[228:231], v157, s[74:75] offset:576 nt
	s_waitcnt vmcnt(7)
	v_pk_fma_f32 v[120:121], v[120:121], v[150:151], v[234:235]
	v_pk_fma_f32 v[118:119], v[118:119], v[148:149], v[232:233]
	global_store_dwordx4 v157, v[118:121], s[76:77] offset:512
	s_add_u32 s74, s74, 0x20000
	s_addc_u32 s75, s75, 0
	global_load_dwordx4 v[232:235], v157, s[74:75] nt
	s_waitcnt vmcnt(8)
	v_pk_fma_f32 v[116:117], v[116:117], v[170:171], v[238:239]
	v_pk_fma_f32 v[114:115], v[114:115], v[168:169], v[236:237]
	global_store_dwordx4 v157, v[114:117], s[76:77] offset:576
	global_load_dwordx4 v[236:239], v157, s[74:75] offset:64 nt
	s_add_u32 s76, s76, 0x20000
	s_addc_u32 s77, s77, 0
	s_waitcnt vmcnt(9)
	v_pk_fma_f32 v[112:113], v[112:113], v[142:143], v[242:243]
	v_pk_fma_f32 v[110:111], v[110:111], v[140:141], v[240:241]
	global_store_dwordx4 v157, v[110:113], s[76:77]
	global_load_dwordx4 v[240:243], v157, s[74:75] offset:512 nt
	s_waitcnt vmcnt(10)
	v_pk_fma_f32 v[108:109], v[108:109], v[146:147], v[246:247]
	v_pk_fma_f32 v[106:107], v[106:107], v[144:145], v[244:245]
	global_store_dwordx4 v157, v[106:109], s[76:77] offset:64
	global_load_dwordx4 v[244:247], v157, s[74:75] offset:576 nt
	s_waitcnt vmcnt(10)
	v_pk_fma_f32 v[104:105], v[104:105], v[150:151], v[226:227]
	v_pk_fma_f32 v[102:103], v[102:103], v[148:149], v[224:225]
	global_store_dwordx4 v157, v[102:105], s[76:77] offset:512
	s_add_u32 s74, s74, 0x20000
	s_addc_u32 s75, s75, 0
	global_load_dwordx4 v[224:227], v157, s[74:75] nt
	s_waitcnt vmcnt(10)
	v_pk_fma_f32 v[100:101], v[100:101], v[170:171], v[230:231]
	v_pk_fma_f32 v[98:99], v[98:99], v[168:169], v[228:229]
	global_store_dwordx4 v157, v[98:101], s[76:77] offset:576
	global_load_dwordx4 v[228:231], v157, s[74:75] offset:64 nt
	s_add_u32 s76, s76, 0x20000
	s_addc_u32 s77, s77, 0
	s_waitcnt vmcnt(10)
	v_pk_fma_f32 v[96:97], v[96:97], v[142:143], v[234:235]
	v_pk_fma_f32 v[94:95], v[94:95], v[140:141], v[232:233]
	global_store_dwordx4 v157, v[94:97], s[76:77]
	global_load_dwordx4 v[232:235], v157, s[74:75] offset:512 nt
	s_waitcnt vmcnt(10)
	v_pk_fma_f32 v[92:93], v[92:93], v[146:147], v[238:239]
	v_pk_fma_f32 v[90:91], v[90:91], v[144:145], v[236:237]
	global_store_dwordx4 v157, v[90:93], s[76:77] offset:64
	global_load_dwordx4 v[236:239], v157, s[74:75] offset:576 nt
	s_waitcnt vmcnt(10)
	v_pk_fma_f32 v[88:89], v[88:89], v[150:151], v[242:243]
	v_pk_fma_f32 v[86:87], v[86:87], v[148:149], v[240:241]
	global_store_dwordx4 v157, v[86:89], s[76:77] offset:512
	s_add_u32 s74, s74, 0xa0000
	s_addc_u32 s75, s75, 0
	global_load_dwordx4 v[240:243], v157, s[74:75] nt
	s_waitcnt vmcnt(10)
	v_pk_fma_f32 v[84:85], v[84:85], v[170:171], v[246:247]
	v_pk_fma_f32 v[82:83], v[82:83], v[168:169], v[244:245]
	global_store_dwordx4 v157, v[82:85], s[76:77] offset:576
	global_load_dwordx4 v[244:247], v157, s[74:75] offset:64 nt
	s_add_u32 s76, s76, 0x20000
	s_addc_u32 s77, s77, 0
	s_waitcnt vmcnt(10)
	v_pk_fma_f32 v[80:81], v[80:81], v[142:143], v[226:227]
	v_pk_fma_f32 v[78:79], v[78:79], v[140:141], v[224:225]
	global_store_dwordx4 v157, v[78:81], s[76:77]
	global_load_dwordx4 v[224:227], v157, s[74:75] offset:512 nt
	s_waitcnt vmcnt(10)
	v_pk_fma_f32 v[76:77], v[76:77], v[146:147], v[230:231]
	v_pk_fma_f32 v[74:75], v[74:75], v[144:145], v[228:229]
	global_store_dwordx4 v157, v[74:77], s[76:77] offset:64
	global_load_dwordx4 v[228:231], v157, s[74:75] offset:576 nt
	s_waitcnt vmcnt(10)
	v_pk_fma_f32 v[72:73], v[72:73], v[150:151], v[234:235]
	v_pk_fma_f32 v[70:71], v[70:71], v[148:149], v[232:233]
	global_store_dwordx4 v157, v[70:73], s[76:77] offset:512
	s_add_u32 s74, s74, 0x20000
	s_addc_u32 s75, s75, 0
	global_load_dwordx4 v[232:235], v157, s[74:75] nt
	s_waitcnt vmcnt(10)
	v_pk_fma_f32 v[68:69], v[68:69], v[170:171], v[238:239]
	v_pk_fma_f32 v[66:67], v[66:67], v[168:169], v[236:237]
	global_store_dwordx4 v157, v[66:69], s[76:77] offset:576
	global_load_dwordx4 v[236:239], v157, s[74:75] offset:64 nt
	s_add_u32 s76, s76, 0xa0000
	s_addc_u32 s77, s77, 0
	s_waitcnt vmcnt(10)
	v_pk_fma_f32 v[64:65], v[64:65], v[142:143], v[242:243]
	v_pk_fma_f32 v[62:63], v[62:63], v[140:141], v[240:241]
	global_store_dwordx4 v157, v[62:65], s[76:77]
	global_load_dwordx4 v[240:243], v157, s[74:75] offset:512 nt
	s_waitcnt vmcnt(10)
	v_pk_fma_f32 v[60:61], v[60:61], v[146:147], v[246:247]
	v_pk_fma_f32 v[58:59], v[58:59], v[144:145], v[244:245]
	global_store_dwordx4 v157, v[58:61], s[76:77] offset:64
	global_load_dwordx4 v[244:247], v157, s[74:75] offset:576 nt
	s_waitcnt vmcnt(10)
	v_pk_fma_f32 v[56:57], v[56:57], v[150:151], v[226:227]
	v_pk_fma_f32 v[54:55], v[54:55], v[148:149], v[224:225]
	global_store_dwordx4 v157, v[54:57], s[76:77] offset:512
	s_add_u32 s74, s74, 0x20000
	s_addc_u32 s75, s75, 0
	global_load_dwordx4 v[224:227], v157, s[74:75] nt
	s_waitcnt vmcnt(10)
	v_pk_fma_f32 v[52:53], v[52:53], v[170:171], v[230:231]
	v_pk_fma_f32 v[50:51], v[50:51], v[168:169], v[228:229]
	global_store_dwordx4 v157, v[50:53], s[76:77] offset:576
	global_load_dwordx4 v[228:231], v157, s[74:75] offset:64 nt
	s_add_u32 s76, s76, 0x20000
	s_addc_u32 s77, s77, 0
	s_waitcnt vmcnt(10)
	v_pk_fma_f32 v[48:49], v[48:49], v[142:143], v[234:235]
	v_pk_fma_f32 v[46:47], v[46:47], v[140:141], v[232:233]
	global_store_dwordx4 v157, v[46:49], s[76:77]
	global_load_dwordx4 v[232:235], v157, s[74:75] offset:512 nt
	s_waitcnt vmcnt(10)
	v_pk_fma_f32 v[44:45], v[44:45], v[146:147], v[238:239]
	v_pk_fma_f32 v[42:43], v[42:43], v[144:145], v[236:237]
	global_store_dwordx4 v157, v[42:45], s[76:77] offset:64
	global_load_dwordx4 v[236:239], v157, s[74:75] offset:576 nt
	s_waitcnt vmcnt(10)
	v_pk_fma_f32 v[40:41], v[40:41], v[150:151], v[242:243]
	v_pk_fma_f32 v[38:39], v[38:39], v[148:149], v[240:241]
	global_store_dwordx4 v157, v[38:41], s[76:77] offset:512
	s_add_u32 s74, s74, 0x20000
	s_addc_u32 s75, s75, 0
	global_load_dwordx4 v[240:243], v157, s[74:75] nt
	s_waitcnt vmcnt(10)
	v_pk_fma_f32 v[36:37], v[36:37], v[170:171], v[246:247]
	v_pk_fma_f32 v[34:35], v[34:35], v[168:169], v[244:245]
	global_store_dwordx4 v157, v[34:37], s[76:77] offset:576
	global_load_dwordx4 v[244:247], v157, s[74:75] offset:64 nt
	s_add_u32 s76, s76, 0x20000
	s_addc_u32 s77, s77, 0
	s_waitcnt vmcnt(10)
	v_pk_fma_f32 v[32:33], v[32:33], v[142:143], v[226:227]
	v_pk_fma_f32 v[30:31], v[30:31], v[140:141], v[224:225]
	global_store_dwordx4 v157, v[30:33], s[76:77]
	global_load_dwordx4 v[224:227], v157, s[74:75] offset:512 nt
	s_waitcnt vmcnt(10)
	v_pk_fma_f32 v[28:29], v[28:29], v[146:147], v[230:231]
	v_pk_fma_f32 v[26:27], v[26:27], v[144:145], v[228:229]
	global_store_dwordx4 v157, v[26:29], s[76:77] offset:64
	global_load_dwordx4 v[228:231], v157, s[74:75] offset:576 nt
	s_waitcnt vmcnt(10)
	v_pk_fma_f32 v[24:25], v[24:25], v[150:151], v[234:235]
	v_pk_fma_f32 v[22:23], v[22:23], v[148:149], v[232:233]
	global_store_dwordx4 v157, v[22:25], s[76:77] offset:512
	s_waitcnt vmcnt(9)
	v_pk_fma_f32 v[20:21], v[20:21], v[170:171], v[238:239]
	v_pk_fma_f32 v[18:19], v[18:19], v[168:169], v[236:237]
	global_store_dwordx4 v157, v[18:21], s[76:77] offset:576
	s_add_u32 s76, s76, 0x20000
	s_addc_u32 s77, s77, 0
	s_waitcnt vmcnt(8)
	v_pk_fma_f32 v[16:17], v[16:17], v[142:143], v[242:243]
	v_pk_fma_f32 v[14:15], v[14:15], v[140:141], v[240:241]
	global_store_dwordx4 v157, v[14:17], s[76:77]
	s_waitcnt vmcnt(7)
	v_pk_fma_f32 v[12:13], v[12:13], v[146:147], v[246:247]
	v_pk_fma_f32 v[10:11], v[10:11], v[144:145], v[244:245]
	global_store_dwordx4 v157, v[10:13], s[76:77] offset:64
	s_waitcnt vmcnt(6)
	v_pk_fma_f32 v[8:9], v[8:9], v[150:151], v[226:227]
	v_pk_fma_f32 v[6:7], v[6:7], v[148:149], v[224:225]
	global_store_dwordx4 v157, v[6:9], s[76:77] offset:512
	s_waitcnt vmcnt(5)
	v_pk_fma_f32 v[4:5], v[4:5], v[170:171], v[230:231]
	v_pk_fma_f32 v[2:3], v[2:3], v[168:169], v[228:229]
	global_store_dwordx4 v157, v[2:5], s[76:77] offset:576
	s_branch .LBB0_269

.LBB0_562:
	v_lshrrev_b32_e32 v17, 1, v166
	v_and_b32_e32 v17, 24, v17
	v_and_b32_e32 v16, 15, v166
	v_lshlrev_b32_e32 v18, 1, v17
	v_lshl_or_b32 v140, s12, 6, v16
	v_lshl_or_b32 v16, v16, 6, v18
	v_lshlrev_b32_e32 v18, 2, v166
	s_lshl_b32 s0, s12, 13
	v_and_b32_e32 v18, 32, v18
	v_lshl_add_u64 v[8:9], s[48:49], 0, v[0:1]
	v_mov_b32_e32 v135, v1
	v_bitop3_b32 v19, v16, s0, v18 bitop3:0xde
	s_lshl_b32 s0, s13, 5
	v_lshl_add_u64 v[10:11], s[48:49], 0, v[134:135]
	v_mov_b32_e32 v131, v1
	s_and_b32 s12, s0, 0x60
	s_add_i32 m0, s54, 0x18000
	v_lshl_add_u64 v[8:9], v[8:9], 0, s[94:95]
	v_lshl_add_u64 v[12:13], s[46:47], 0, v[130:131]
	v_mov_b32_e32 v133, v1
	s_lshl_b32 s0, s12, 7
	s_waitcnt vmcnt(4)
	s_barrier
	global_load_lds_dwordx4 v[8:9], off
	v_lshl_add_u64 v[8:9], v[10:11], 0, s[94:95]
	s_add_i32 m0, s54, 0x1a000
	s_add_i32 s59, s54, 0x8000
	s_add_i32 s60, s54, 0xa000
	v_lshl_add_u64 v[14:15], s[46:47], 0, v[132:133]
	v_bitop3_b32 v141, s0, v16, v18 bitop3:0xf6
	v_add_u32_e32 v141, 0x10000, v141
	global_load_lds_dwordx4 v[8:9], off
	v_lshl_add_u64 v[8:9], v[12:13], 0, s[94:95]
	s_mov_b32 m0, s59
	s_add_u32 s0, s48, 0x80080
	global_load_lds_dwordx4 v[8:9], off
	v_lshl_add_u64 v[8:9], v[14:15], 0, s[94:95]
	s_mov_b32 m0, s60
	s_addc_u32 s1, s49, 0
	global_load_lds_dwordx4 v[8:9], off
	s_add_i32 m0, s54, 0x1c000
	v_lshl_add_u64 v[8:9], s[0:1], 0, v[0:1]
	global_load_lds_dwordx4 v[8:9], off
	v_lshl_add_u64 v[8:9], s[0:1], 0, v[134:135]
	s_add_i32 m0, s54, 0x1e000
	v_or_b32_e32 v142, s12, v17
	global_load_lds_dwordx4 v[8:9], off
	v_lshlrev_b32_e32 v8, 15, v2
	v_and_b32_e32 v8, 0xffff0000, v8
	v_lshl_add_u32 v3, v3, 12, v8
	v_and_b32_e32 v2, 1, v2
	v_lshl_or_b32 v2, v2, 6, v3
	v_lshl_add_u32 v136, v4, 1, v2
	v_lshlrev_b32_e32 v2, 15, v5
	v_and_b32_e32 v2, 0xffff0000, v2
	s_waitcnt vmcnt(6)
	v_lshl_add_u32 v2, v6, 12, v2
	v_and_b32_e32 v3, 1, v5
	v_lshl_or_b32 v2, v3, 6, v2
	v_mov_b32_e32 v137, v1
	v_lshl_add_u32 v138, v7, 1, v2
	v_mov_b32_e32 v139, v1
	s_mov_b32 s63, 0
	v_add_u32_e32 v143, 0, v19
	s_mov_b64 s[42:43], s[46:47]
	s_mov_b64 s[44:45], s[48:49]
	s_barrier
	s_branch .LBB0_565

.LBB0_572:
	s_add_u32 s41, s46, 0xfff80080
	s_addc_u32 s48, s47, -1
	s_add_i32 s64, 0, 0x10000
	ds_read_b128 v[144:147], v141
	ds_read_b128 v[148:151], v141 offset:1024
	ds_read_b128 v[152:155], v141 offset:2048
	ds_read_b128 v[168:171], v141 offset:3072
	s_cmp_eq_u32 s39, 28
	s_cselect_b32 s51, s43, s48
	s_cselect_b32 s50, s42, s41
	s_cselect_b32 s49, s45, s13
	s_cselect_b32 s48, s44, s12
	s_add_i32 m0, s54, 0xc000
	ds_read_b128 v[172:175], v143
	ds_read_b128 v[176:179], v143 offset:1024
	ds_read_b128 v[180:183], v143 offset:2048
	ds_read_b128 v[184:187], v143 offset:3072
	ds_read_b128 v[188:191], v143 offset:4096
	ds_read_b128 v[192:195], v143 offset:5120
	ds_read_b128 v[196:199], v143 offset:6144
	ds_read_b128 v[224:227], v143 offset:7168
	global_load_lds_dwordx4 v136, s[46:47]
	s_add_i32 m0, s54, 0xe000
	s_nop 0
	global_load_lds_dwordx4 v138, s[46:47]
	s_waitcnt lgkmcnt(8)
	s_barrier
	s_waitcnt lgkmcnt(0)
	s_waitcnt lgkmcnt(0)
	v_mfma_f32_16x16x32_bf16 v[126:129], v[144:147], v[172:175], v[126:129]
	v_mfma_f32_16x16x32_bf16 v[122:125], v[152:155], v[172:175], v[122:125]
	v_mfma_f32_16x16x32_bf16 v[118:121], v[144:147], v[180:183], v[118:121]
	v_mfma_f32_16x16x32_bf16 v[114:117], v[152:155], v[180:183], v[114:117]
	v_mfma_f32_16x16x32_bf16 v[102:105], v[144:147], v[188:191], v[102:105]
	v_mfma_f32_16x16x32_bf16 v[98:101], v[152:155], v[188:191], v[98:101]
	v_mfma_f32_16x16x32_bf16 v[86:89], v[144:147], v[196:199], v[86:89]
	v_mfma_f32_16x16x32_bf16 v[82:85], v[152:155], v[196:199], v[82:85]
	v_mfma_f32_16x16x32_bf16 v[126:129], v[148:151], v[176:179], v[126:129]
	v_mfma_f32_16x16x32_bf16 v[122:125], v[168:171], v[176:179], v[122:125]
	v_mfma_f32_16x16x32_bf16 v[118:121], v[148:151], v[184:187], v[118:121]
	v_mfma_f32_16x16x32_bf16 v[114:117], v[168:171], v[184:187], v[114:117]
	v_mfma_f32_16x16x32_bf16 v[102:105], v[148:151], v[192:195], v[102:105]
	v_mfma_f32_16x16x32_bf16 v[98:101], v[168:171], v[192:195], v[98:101]
	v_mfma_f32_16x16x32_bf16 v[86:89], v[148:151], v[224:227], v[86:89]
	v_mfma_f32_16x16x32_bf16 v[82:85], v[168:171], v[224:227], v[82:85]
	s_barrier
	s_add_i32 s41, 0, 0x14000
	s_add_i32 s64, s64, s53
	ds_read_b128 v[228:231], v141 offset:16384
	ds_read_b128 v[232:235], v141 offset:17408
	ds_read_b128 v[236:239], v141 offset:18432
	ds_read_b128 v[240:243], v141 offset:19456
	s_add_u32 s76, s48, s94
	s_addc_u32 s77, s49, s95
	s_mov_b32 m0, s64
	s_nop 0
	global_load_lds_dwordx4 v0, s[48:49]
	s_add_i32 m0, s64, 0x2000
	s_nop 0
	global_load_lds_dwordx4 v134, s[48:49]
	s_barrier
	s_waitcnt lgkmcnt(0)
	s_waitcnt lgkmcnt(0)
	v_mfma_f32_16x16x32_bf16 v[110:113], v[228:231], v[172:175], v[110:113]
	v_mfma_f32_16x16x32_bf16 v[106:109], v[236:239], v[172:175], v[106:109]
	v_mfma_f32_16x16x32_bf16 v[94:97], v[228:231], v[180:183], v[94:97]
	v_mfma_f32_16x16x32_bf16 v[90:93], v[236:239], v[180:183], v[90:93]
	v_mfma_f32_16x16x32_bf16 v[78:81], v[228:231], v[188:191], v[78:81]
	v_mfma_f32_16x16x32_bf16 v[74:77], v[236:239], v[188:191], v[74:77]
	v_mfma_f32_16x16x32_bf16 v[70:73], v[228:231], v[196:199], v[70:73]
	v_mfma_f32_16x16x32_bf16 v[66:69], v[236:239], v[196:199], v[66:69]
	v_mfma_f32_16x16x32_bf16 v[110:113], v[232:235], v[176:179], v[110:113]
	v_mfma_f32_16x16x32_bf16 v[106:109], v[240:243], v[176:179], v[106:109]
	v_mfma_f32_16x16x32_bf16 v[94:97], v[232:235], v[184:187], v[94:97]
	v_mfma_f32_16x16x32_bf16 v[90:93], v[240:243], v[184:187], v[90:93]
	v_mfma_f32_16x16x32_bf16 v[78:81], v[232:235], v[192:195], v[78:81]
	v_mfma_f32_16x16x32_bf16 v[74:77], v[240:243], v[192:195], v[74:77]
	v_mfma_f32_16x16x32_bf16 v[70:73], v[232:235], v[224:227], v[70:73]
	v_mfma_f32_16x16x32_bf16 v[66:69], v[240:243], v[224:227], v[66:69]
	s_mov_b32 m0, s54
	s_add_u32 s78, s50, s94
	s_addc_u32 s79, s51, s95
	s_barrier
	ds_read_b128 v[172:175], v143 offset:16384
	ds_read_b128 v[176:179], v143 offset:17408
	ds_read_b128 v[180:183], v143 offset:18432
	ds_read_b128 v[184:187], v143 offset:19456
	ds_read_b128 v[188:191], v143 offset:20480
	ds_read_b128 v[192:195], v143 offset:21504
	ds_read_b128 v[196:199], v143 offset:22528
	ds_read_b128 v[224:227], v143 offset:23552
	global_load_lds_dwordx4 v130, s[50:51]
	s_mov_b32 m0, s55
	s_nop 0
	global_load_lds_dwordx4 v132, s[50:51]
	s_barrier
	s_waitcnt lgkmcnt(0)
	s_waitcnt lgkmcnt(0)
	v_mfma_f32_16x16x32_bf16 v[62:65], v[144:147], v[172:175], v[62:65]
	v_mfma_f32_16x16x32_bf16 v[58:61], v[152:155], v[172:175], v[58:61]
	v_mfma_f32_16x16x32_bf16 v[54:57], v[144:147], v[180:183], v[54:57]
	v_mfma_f32_16x16x32_bf16 v[50:53], v[152:155], v[180:183], v[50:53]
	v_mfma_f32_16x16x32_bf16 v[38:41], v[144:147], v[188:191], v[38:41]
	v_mfma_f32_16x16x32_bf16 v[34:37], v[152:155], v[188:191], v[34:37]
	v_mfma_f32_16x16x32_bf16 v[22:25], v[144:147], v[196:199], v[22:25]
	v_mfma_f32_16x16x32_bf16 v[18:21], v[152:155], v[196:199], v[18:21]
	v_mfma_f32_16x16x32_bf16 v[62:65], v[148:151], v[176:179], v[62:65]
	v_mfma_f32_16x16x32_bf16 v[58:61], v[168:171], v[176:179], v[58:61]
	v_mfma_f32_16x16x32_bf16 v[54:57], v[148:151], v[184:187], v[54:57]
	v_mfma_f32_16x16x32_bf16 v[50:53], v[168:171], v[184:187], v[50:53]
	v_mfma_f32_16x16x32_bf16 v[38:41], v[148:151], v[192:195], v[38:41]
	v_mfma_f32_16x16x32_bf16 v[34:37], v[168:171], v[192:195], v[34:37]
	v_mfma_f32_16x16x32_bf16 v[22:25], v[148:151], v[224:227], v[22:25]
	v_mfma_f32_16x16x32_bf16 v[18:21], v[168:171], v[224:227], v[18:21]
	s_barrier
	s_add_u32 s64, s48, 0x80000
	s_addc_u32 s65, s49, 0
	s_add_i32 s41, s41, s53
	s_mov_b32 m0, s41
	s_nop 0
	global_load_lds_dwordx4 v0, s[64:65]
	s_add_i32 m0, s41, 0x2000
	s_nop 0
	global_load_lds_dwordx4 v134, s[64:65]
	s_waitcnt vmcnt(6)
	s_barrier
	v_mfma_f32_16x16x32_bf16 v[46:49], v[228:231], v[172:175], v[46:49]
	v_mfma_f32_16x16x32_bf16 v[42:45], v[236:239], v[172:175], v[42:45]
	v_mfma_f32_16x16x32_bf16 v[30:33], v[228:231], v[180:183], v[30:33]
	v_mfma_f32_16x16x32_bf16 v[26:29], v[236:239], v[180:183], v[26:29]
	v_mfma_f32_16x16x32_bf16 v[14:17], v[228:231], v[188:191], v[14:17]
	v_mfma_f32_16x16x32_bf16 v[10:13], v[236:239], v[188:191], v[10:13]
	v_mfma_f32_16x16x32_bf16 v[6:9], v[228:231], v[196:199], v[6:9]
	v_mfma_f32_16x16x32_bf16 v[2:5], v[236:239], v[196:199], v[2:5]
	v_mfma_f32_16x16x32_bf16 v[46:49], v[232:235], v[176:179], v[46:49]
	v_mfma_f32_16x16x32_bf16 v[42:45], v[240:243], v[176:179], v[42:45]
	v_mfma_f32_16x16x32_bf16 v[30:33], v[232:235], v[184:187], v[30:33]
	v_mfma_f32_16x16x32_bf16 v[26:29], v[240:243], v[184:187], v[26:29]
	v_mfma_f32_16x16x32_bf16 v[14:17], v[232:235], v[192:195], v[14:17]
	v_mfma_f32_16x16x32_bf16 v[10:13], v[240:243], v[192:195], v[10:13]
	v_mfma_f32_16x16x32_bf16 v[6:9], v[232:235], v[224:227], v[6:9]
	v_mfma_f32_16x16x32_bf16 v[2:5], v[240:243], v[224:227], v[2:5]
	s_add_i32 s41, 0, 0x18000
	s_barrier
	ds_read_b128 v[144:147], v141 offset:32768
	ds_read_b128 v[148:151], v141 offset:33792
	ds_read_b128 v[152:155], v141 offset:34816
	ds_read_b128 v[168:171], v141 offset:35840
	s_add_u32 s50, s50, 0x80000
	s_addc_u32 s51, s51, 0
	s_mov_b32 m0, s56
	ds_read_b128 v[172:175], v143 offset:32768
	ds_read_b128 v[176:179], v143 offset:33792
	ds_read_b128 v[180:183], v143 offset:34816
	ds_read_b128 v[184:187], v143 offset:35840
	ds_read_b128 v[188:191], v143 offset:36864
	ds_read_b128 v[192:195], v143 offset:37888
	ds_read_b128 v[196:199], v143 offset:38912
	ds_read_b128 v[224:227], v143 offset:39936
	global_load_lds_dwordx4 v130, s[50:51]
	s_mov_b32 m0, s57
	s_nop 0
	global_load_lds_dwordx4 v132, s[50:51]
	s_waitcnt lgkmcnt(8)
	s_barrier
	s_waitcnt lgkmcnt(0)
	s_waitcnt lgkmcnt(0)
	v_mfma_f32_16x16x32_bf16 v[126:129], v[144:147], v[172:175], v[126:129]
	v_mfma_f32_16x16x32_bf16 v[122:125], v[152:155], v[172:175], v[122:125]
	v_mfma_f32_16x16x32_bf16 v[118:121], v[144:147], v[180:183], v[118:121]
	v_mfma_f32_16x16x32_bf16 v[114:117], v[152:155], v[180:183], v[114:117]
	v_mfma_f32_16x16x32_bf16 v[102:105], v[144:147], v[188:191], v[102:105]
	v_mfma_f32_16x16x32_bf16 v[98:101], v[152:155], v[188:191], v[98:101]
	v_mfma_f32_16x16x32_bf16 v[86:89], v[144:147], v[196:199], v[86:89]
	v_mfma_f32_16x16x32_bf16 v[82:85], v[152:155], v[196:199], v[82:85]
	v_mfma_f32_16x16x32_bf16 v[126:129], v[148:151], v[176:179], v[126:129]
	v_mfma_f32_16x16x32_bf16 v[122:125], v[168:171], v[176:179], v[122:125]
	v_mfma_f32_16x16x32_bf16 v[118:121], v[148:151], v[184:187], v[118:121]
	v_mfma_f32_16x16x32_bf16 v[114:117], v[168:171], v[184:187], v[114:117]
	v_mfma_f32_16x16x32_bf16 v[102:105], v[148:151], v[192:195], v[102:105]
	v_mfma_f32_16x16x32_bf16 v[98:101], v[168:171], v[192:195], v[98:101]
	v_mfma_f32_16x16x32_bf16 v[86:89], v[148:151], v[224:227], v[86:89]
	v_mfma_f32_16x16x32_bf16 v[82:85], v[168:171], v[224:227], v[82:85]
	s_barrier
	s_add_i32 s50, 0, 0x1c000
	s_add_i32 s41, s41, s53
	s_mov_b32 m0, s41
	ds_read_b128 v[228:231], v141 offset:49152
	ds_read_b128 v[232:235], v141 offset:50176
	ds_read_b128 v[236:239], v141 offset:51200
	ds_read_b128 v[240:243], v141 offset:52224
	global_load_lds_dwordx4 v0, s[76:77]
	s_add_i32 m0, s41, 0x2000
	s_nop 0
	global_load_lds_dwordx4 v134, s[76:77]
	s_barrier
	s_waitcnt lgkmcnt(0)
	s_waitcnt lgkmcnt(0)
	v_mfma_f32_16x16x32_bf16 v[110:113], v[228:231], v[172:175], v[110:113]
	v_mfma_f32_16x16x32_bf16 v[106:109], v[236:239], v[172:175], v[106:109]
	v_mfma_f32_16x16x32_bf16 v[94:97], v[228:231], v[180:183], v[94:97]
	v_mfma_f32_16x16x32_bf16 v[90:93], v[236:239], v[180:183], v[90:93]
	v_mfma_f32_16x16x32_bf16 v[78:81], v[228:231], v[188:191], v[78:81]
	v_mfma_f32_16x16x32_bf16 v[74:77], v[236:239], v[188:191], v[74:77]
	v_mfma_f32_16x16x32_bf16 v[70:73], v[228:231], v[196:199], v[70:73]
	v_mfma_f32_16x16x32_bf16 v[66:69], v[236:239], v[196:199], v[66:69]
	v_mfma_f32_16x16x32_bf16 v[110:113], v[232:235], v[176:179], v[110:113]
	v_mfma_f32_16x16x32_bf16 v[106:109], v[240:243], v[176:179], v[106:109]
	v_mfma_f32_16x16x32_bf16 v[94:97], v[232:235], v[184:187], v[94:97]
	v_mfma_f32_16x16x32_bf16 v[90:93], v[240:243], v[184:187], v[90:93]
	v_mfma_f32_16x16x32_bf16 v[78:81], v[232:235], v[192:195], v[78:81]
	v_mfma_f32_16x16x32_bf16 v[74:77], v[240:243], v[192:195], v[74:77]
	v_mfma_f32_16x16x32_bf16 v[70:73], v[232:235], v[224:227], v[70:73]
	v_mfma_f32_16x16x32_bf16 v[66:69], v[240:243], v[224:227], v[66:69]
	s_mov_b32 m0, s59
	s_barrier
	ds_read_b128 v[172:175], v143 offset:49152
	ds_read_b128 v[176:179], v143 offset:50176
	ds_read_b128 v[180:183], v143 offset:51200
	ds_read_b128 v[184:187], v143 offset:52224
	ds_read_b128 v[188:191], v143 offset:53248
	ds_read_b128 v[192:195], v143 offset:54272
	ds_read_b128 v[196:199], v143 offset:55296
	ds_read_b128 v[224:227], v143 offset:56320
	global_load_lds_dwordx4 v130, s[78:79]
	s_mov_b32 m0, s60
	s_nop 0
	global_load_lds_dwordx4 v132, s[78:79]
	s_barrier
	s_waitcnt lgkmcnt(0)
	s_waitcnt lgkmcnt(0)
	v_mfma_f32_16x16x32_bf16 v[62:65], v[144:147], v[172:175], v[62:65]
	v_mfma_f32_16x16x32_bf16 v[58:61], v[152:155], v[172:175], v[58:61]
	v_mfma_f32_16x16x32_bf16 v[54:57], v[144:147], v[180:183], v[54:57]
	v_mfma_f32_16x16x32_bf16 v[50:53], v[152:155], v[180:183], v[50:53]
	v_mfma_f32_16x16x32_bf16 v[38:41], v[144:147], v[188:191], v[38:41]
	v_mfma_f32_16x16x32_bf16 v[34:37], v[152:155], v[188:191], v[34:37]
	v_mfma_f32_16x16x32_bf16 v[22:25], v[144:147], v[196:199], v[22:25]
	v_mfma_f32_16x16x32_bf16 v[18:21], v[152:155], v[196:199], v[18:21]
	v_mfma_f32_16x16x32_bf16 v[62:65], v[148:151], v[176:179], v[62:65]
	v_mfma_f32_16x16x32_bf16 v[58:61], v[168:171], v[176:179], v[58:61]
	v_mfma_f32_16x16x32_bf16 v[54:57], v[148:151], v[184:187], v[54:57]
	v_mfma_f32_16x16x32_bf16 v[50:53], v[168:171], v[184:187], v[50:53]
	v_mfma_f32_16x16x32_bf16 v[38:41], v[148:151], v[192:195], v[38:41]
	v_mfma_f32_16x16x32_bf16 v[34:37], v[168:171], v[192:195], v[34:37]
	v_mfma_f32_16x16x32_bf16 v[22:25], v[148:151], v[224:227], v[22:25]
	v_mfma_f32_16x16x32_bf16 v[18:21], v[168:171], v[224:227], v[18:21]
	s_barrier
	s_add_u32 s48, s48, 0x80080
	s_addc_u32 s49, s49, 0
	s_add_i32 s41, s50, s53
	s_mov_b32 m0, s41
	s_nop 0
	global_load_lds_dwordx4 v0, s[48:49]
	s_add_i32 m0, s41, 0x2000
	s_nop 0
	global_load_lds_dwordx4 v134, s[48:49]
	s_waitcnt vmcnt(6)
	s_barrier
	v_mfma_f32_16x16x32_bf16 v[46:49], v[228:231], v[172:175], v[46:49]
	v_mfma_f32_16x16x32_bf16 v[42:45], v[236:239], v[172:175], v[42:45]
	v_mfma_f32_16x16x32_bf16 v[30:33], v[228:231], v[180:183], v[30:33]
	v_mfma_f32_16x16x32_bf16 v[26:29], v[236:239], v[180:183], v[26:29]
	v_mfma_f32_16x16x32_bf16 v[14:17], v[228:231], v[188:191], v[14:17]
	v_mfma_f32_16x16x32_bf16 v[10:13], v[236:239], v[188:191], v[10:13]
	v_mfma_f32_16x16x32_bf16 v[6:9], v[228:231], v[196:199], v[6:9]
	v_mfma_f32_16x16x32_bf16 v[2:5], v[236:239], v[196:199], v[2:5]
	v_mfma_f32_16x16x32_bf16 v[46:49], v[232:235], v[176:179], v[46:49]
	v_mfma_f32_16x16x32_bf16 v[42:45], v[240:243], v[176:179], v[42:45]
	v_mfma_f32_16x16x32_bf16 v[30:33], v[232:235], v[184:187], v[30:33]
	v_mfma_f32_16x16x32_bf16 v[26:29], v[240:243], v[184:187], v[26:29]
	v_mfma_f32_16x16x32_bf16 v[14:17], v[232:235], v[192:195], v[14:17]
	v_mfma_f32_16x16x32_bf16 v[10:13], v[240:243], v[192:195], v[10:13]
	v_mfma_f32_16x16x32_bf16 v[6:9], v[232:235], v[224:227], v[6:9]
	v_mfma_f32_16x16x32_bf16 v[2:5], v[240:243], v[224:227], v[2:5]
	s_add_i32 s39, s39, 2
	s_add_u32 s46, s46, 0x100
	s_addc_u32 s47, s47, 0
	s_add_u32 s12, s12, 0x100
	s_addc_u32 s13, s13, 0
	s_cmp_gt_u32 s39, 29
	s_barrier
	s_cbranch_scc0 .LBB0_572
	s_cmp_lg_u32 s62, 0
	s_cbranch_scc0 .LBB0_575
	s_lshl_b32 s39, s61, 8
	s_mov_b64 s[12:13], 0
	s_branch .LBB0_576

.LBB0_774:
	v_lshrrev_b32_e32 v17, 1, v166
	v_and_b32_e32 v17, 24, v17
	v_and_b32_e32 v16, 15, v166
	v_lshlrev_b32_e32 v18, 1, v17
	v_lshl_or_b32 v140, s12, 6, v16
	v_lshl_or_b32 v16, v16, 6, v18
	v_lshlrev_b32_e32 v18, 2, v166
	s_lshl_b32 s0, s12, 13
	v_and_b32_e32 v18, 32, v18
	v_lshl_add_u64 v[8:9], s[48:49], 0, v[0:1]
	v_mov_b32_e32 v135, v1
	v_bitop3_b32 v19, v16, s0, v18 bitop3:0xde
	s_lshl_b32 s0, s13, 5
	v_lshl_add_u64 v[10:11], s[48:49], 0, v[134:135]
	v_mov_b32_e32 v131, v1
	s_and_b32 s12, s0, 0x60
	s_add_i32 m0, s54, 0x18000
	v_lshl_add_u64 v[8:9], v[8:9], 0, s[94:95]
	v_lshl_add_u64 v[12:13], s[46:47], 0, v[130:131]
	v_mov_b32_e32 v133, v1
	s_lshl_b32 s0, s12, 7
	s_waitcnt vmcnt(4)
	s_barrier
	global_load_lds_dwordx4 v[8:9], off
	v_lshl_add_u64 v[8:9], v[10:11], 0, s[94:95]
	s_add_i32 m0, s54, 0x1a000
	s_add_i32 s59, s54, 0x8000
	s_add_i32 s61, s54, 0xa000
	v_lshl_add_u64 v[14:15], s[46:47], 0, v[132:133]
	v_bitop3_b32 v141, s0, v16, v18 bitop3:0xf6
	v_add_u32_e32 v141, 0x10000, v141
	global_load_lds_dwordx4 v[8:9], off
	v_lshl_add_u64 v[8:9], v[12:13], 0, s[94:95]
	s_mov_b32 m0, s59
	s_add_u32 s0, s48, 0x80080
	global_load_lds_dwordx4 v[8:9], off
	v_lshl_add_u64 v[8:9], v[14:15], 0, s[94:95]
	s_mov_b32 m0, s61
	s_addc_u32 s1, s49, 0
	global_load_lds_dwordx4 v[8:9], off
	s_add_i32 m0, s54, 0x1c000
	v_lshl_add_u64 v[8:9], s[0:1], 0, v[0:1]
	global_load_lds_dwordx4 v[8:9], off
	v_lshl_add_u64 v[8:9], s[0:1], 0, v[134:135]
	s_add_i32 m0, s54, 0x1e000
	v_or_b32_e32 v142, s12, v17
	global_load_lds_dwordx4 v[8:9], off
	v_lshlrev_b32_e32 v8, 15, v2
	v_and_b32_e32 v8, 0xffff0000, v8
	v_lshl_add_u32 v3, v3, 12, v8
	v_and_b32_e32 v2, 1, v2
	v_lshl_or_b32 v2, v2, 6, v3
	v_lshl_add_u32 v136, v4, 1, v2
	v_lshlrev_b32_e32 v2, 15, v5
	v_and_b32_e32 v2, 0xffff0000, v2
	s_waitcnt vmcnt(6)
	v_lshl_add_u32 v2, v6, 12, v2
	v_and_b32_e32 v3, 1, v5
	v_lshl_or_b32 v2, v3, 6, v2
	v_mov_b32_e32 v137, v1
	v_lshl_add_u32 v138, v7, 1, v2
	v_mov_b32_e32 v139, v1
	s_mov_b32 s63, 0
	v_add_u32_e32 v143, 0, v19
	s_barrier
	s_branch .LBB0_777

.LBB0_788:
	s_add_u32 s39, s46, 0xfff80080
	s_addc_u32 s48, s47, -1
	s_add_i32 s64, 0, 0x10000
	ds_read_b128 v[144:147], v141
	ds_read_b128 v[148:151], v141 offset:1024
	ds_read_b128 v[152:155], v141 offset:2048
	ds_read_b128 v[168:171], v141 offset:3072
	s_cmp_eq_u32 s13, 28
	s_cselect_b32 s51, s43, s48
	s_cselect_b32 s50, s42, s39
	s_cselect_b32 s49, s45, s12
	s_cselect_b32 s48, s44, s1
	s_add_i32 m0, s54, 0xc000
	ds_read_b128 v[172:175], v143
	ds_read_b128 v[176:179], v143 offset:1024
	ds_read_b128 v[180:183], v143 offset:2048
	ds_read_b128 v[184:187], v143 offset:3072
	ds_read_b128 v[188:191], v143 offset:4096
	ds_read_b128 v[192:195], v143 offset:5120
	ds_read_b128 v[196:199], v143 offset:6144
	ds_read_b128 v[224:227], v143 offset:7168
	global_load_lds_dwordx4 v136, s[46:47]
	s_add_i32 m0, s54, 0xe000
	s_nop 0
	global_load_lds_dwordx4 v138, s[46:47]
	s_waitcnt lgkmcnt(8)
	s_barrier
	s_waitcnt lgkmcnt(0)
	s_waitcnt lgkmcnt(0)
	v_mfma_f32_16x16x32_bf16 v[126:129], v[144:147], v[172:175], v[126:129]
	v_mfma_f32_16x16x32_bf16 v[122:125], v[152:155], v[172:175], v[122:125]
	v_mfma_f32_16x16x32_bf16 v[118:121], v[144:147], v[180:183], v[118:121]
	v_mfma_f32_16x16x32_bf16 v[114:117], v[152:155], v[180:183], v[114:117]
	v_mfma_f32_16x16x32_bf16 v[102:105], v[144:147], v[188:191], v[102:105]
	v_mfma_f32_16x16x32_bf16 v[98:101], v[152:155], v[188:191], v[98:101]
	v_mfma_f32_16x16x32_bf16 v[86:89], v[144:147], v[196:199], v[86:89]
	v_mfma_f32_16x16x32_bf16 v[82:85], v[152:155], v[196:199], v[82:85]
	v_mfma_f32_16x16x32_bf16 v[126:129], v[148:151], v[176:179], v[126:129]
	v_mfma_f32_16x16x32_bf16 v[122:125], v[168:171], v[176:179], v[122:125]
	v_mfma_f32_16x16x32_bf16 v[118:121], v[148:151], v[184:187], v[118:121]
	v_mfma_f32_16x16x32_bf16 v[114:117], v[168:171], v[184:187], v[114:117]
	v_mfma_f32_16x16x32_bf16 v[102:105], v[148:151], v[192:195], v[102:105]
	v_mfma_f32_16x16x32_bf16 v[98:101], v[168:171], v[192:195], v[98:101]
	v_mfma_f32_16x16x32_bf16 v[86:89], v[148:151], v[224:227], v[86:89]
	v_mfma_f32_16x16x32_bf16 v[82:85], v[168:171], v[224:227], v[82:85]
	s_barrier
	s_add_i32 s39, 0, 0x14000
	s_add_i32 s64, s64, s53
	ds_read_b128 v[228:231], v141 offset:16384
	ds_read_b128 v[232:235], v141 offset:17408
	ds_read_b128 v[236:239], v141 offset:18432
	ds_read_b128 v[240:243], v141 offset:19456
	s_add_u32 s76, s48, s94
	s_addc_u32 s77, s49, s95
	s_mov_b32 m0, s64
	s_nop 0
	global_load_lds_dwordx4 v0, s[48:49]
	s_add_i32 m0, s64, 0x2000
	s_nop 0
	global_load_lds_dwordx4 v134, s[48:49]
	s_barrier
	s_waitcnt lgkmcnt(0)
	s_waitcnt lgkmcnt(0)
	v_mfma_f32_16x16x32_bf16 v[110:113], v[228:231], v[172:175], v[110:113]
	v_mfma_f32_16x16x32_bf16 v[106:109], v[236:239], v[172:175], v[106:109]
	v_mfma_f32_16x16x32_bf16 v[94:97], v[228:231], v[180:183], v[94:97]
	v_mfma_f32_16x16x32_bf16 v[90:93], v[236:239], v[180:183], v[90:93]
	v_mfma_f32_16x16x32_bf16 v[78:81], v[228:231], v[188:191], v[78:81]
	v_mfma_f32_16x16x32_bf16 v[74:77], v[236:239], v[188:191], v[74:77]
	v_mfma_f32_16x16x32_bf16 v[70:73], v[228:231], v[196:199], v[70:73]
	v_mfma_f32_16x16x32_bf16 v[66:69], v[236:239], v[196:199], v[66:69]
	v_mfma_f32_16x16x32_bf16 v[110:113], v[232:235], v[176:179], v[110:113]
	v_mfma_f32_16x16x32_bf16 v[106:109], v[240:243], v[176:179], v[106:109]
	v_mfma_f32_16x16x32_bf16 v[94:97], v[232:235], v[184:187], v[94:97]
	v_mfma_f32_16x16x32_bf16 v[90:93], v[240:243], v[184:187], v[90:93]
	v_mfma_f32_16x16x32_bf16 v[78:81], v[232:235], v[192:195], v[78:81]
	v_mfma_f32_16x16x32_bf16 v[74:77], v[240:243], v[192:195], v[74:77]
	v_mfma_f32_16x16x32_bf16 v[70:73], v[232:235], v[224:227], v[70:73]
	v_mfma_f32_16x16x32_bf16 v[66:69], v[240:243], v[224:227], v[66:69]
	s_mov_b32 m0, s54
	s_add_u32 s78, s50, s94
	s_addc_u32 s79, s51, s95
	s_barrier
	ds_read_b128 v[172:175], v143 offset:16384
	ds_read_b128 v[176:179], v143 offset:17408
	ds_read_b128 v[180:183], v143 offset:18432
	ds_read_b128 v[184:187], v143 offset:19456
	ds_read_b128 v[188:191], v143 offset:20480
	ds_read_b128 v[192:195], v143 offset:21504
	ds_read_b128 v[196:199], v143 offset:22528
	ds_read_b128 v[224:227], v143 offset:23552
	global_load_lds_dwordx4 v130, s[50:51]
	s_mov_b32 m0, s55
	s_nop 0
	global_load_lds_dwordx4 v132, s[50:51]
	s_barrier
	s_waitcnt lgkmcnt(0)
	s_waitcnt lgkmcnt(0)
	v_mfma_f32_16x16x32_bf16 v[62:65], v[144:147], v[172:175], v[62:65]
	v_mfma_f32_16x16x32_bf16 v[58:61], v[152:155], v[172:175], v[58:61]
	v_mfma_f32_16x16x32_bf16 v[54:57], v[144:147], v[180:183], v[54:57]
	v_mfma_f32_16x16x32_bf16 v[50:53], v[152:155], v[180:183], v[50:53]
	v_mfma_f32_16x16x32_bf16 v[38:41], v[144:147], v[188:191], v[38:41]
	v_mfma_f32_16x16x32_bf16 v[34:37], v[152:155], v[188:191], v[34:37]
	v_mfma_f32_16x16x32_bf16 v[22:25], v[144:147], v[196:199], v[22:25]
	v_mfma_f32_16x16x32_bf16 v[18:21], v[152:155], v[196:199], v[18:21]
	v_mfma_f32_16x16x32_bf16 v[62:65], v[148:151], v[176:179], v[62:65]
	v_mfma_f32_16x16x32_bf16 v[58:61], v[168:171], v[176:179], v[58:61]
	v_mfma_f32_16x16x32_bf16 v[54:57], v[148:151], v[184:187], v[54:57]
	v_mfma_f32_16x16x32_bf16 v[50:53], v[168:171], v[184:187], v[50:53]
	v_mfma_f32_16x16x32_bf16 v[38:41], v[148:151], v[192:195], v[38:41]
	v_mfma_f32_16x16x32_bf16 v[34:37], v[168:171], v[192:195], v[34:37]
	v_mfma_f32_16x16x32_bf16 v[22:25], v[148:151], v[224:227], v[22:25]
	v_mfma_f32_16x16x32_bf16 v[18:21], v[168:171], v[224:227], v[18:21]
	s_barrier
	s_add_u32 s64, s48, 0x80000
	s_addc_u32 s65, s49, 0
	s_add_i32 s39, s39, s53
	s_mov_b32 m0, s39
	s_nop 0
	global_load_lds_dwordx4 v0, s[64:65]
	s_add_i32 m0, s39, 0x2000
	s_nop 0
	global_load_lds_dwordx4 v134, s[64:65]
	s_waitcnt vmcnt(6)
	s_barrier
	v_mfma_f32_16x16x32_bf16 v[46:49], v[228:231], v[172:175], v[46:49]
	v_mfma_f32_16x16x32_bf16 v[42:45], v[236:239], v[172:175], v[42:45]
	v_mfma_f32_16x16x32_bf16 v[30:33], v[228:231], v[180:183], v[30:33]
	v_mfma_f32_16x16x32_bf16 v[26:29], v[236:239], v[180:183], v[26:29]
	v_mfma_f32_16x16x32_bf16 v[14:17], v[228:231], v[188:191], v[14:17]
	v_mfma_f32_16x16x32_bf16 v[10:13], v[236:239], v[188:191], v[10:13]
	v_mfma_f32_16x16x32_bf16 v[6:9], v[228:231], v[196:199], v[6:9]
	v_mfma_f32_16x16x32_bf16 v[2:5], v[236:239], v[196:199], v[2:5]
	v_mfma_f32_16x16x32_bf16 v[46:49], v[232:235], v[176:179], v[46:49]
	v_mfma_f32_16x16x32_bf16 v[42:45], v[240:243], v[176:179], v[42:45]
	v_mfma_f32_16x16x32_bf16 v[30:33], v[232:235], v[184:187], v[30:33]
	v_mfma_f32_16x16x32_bf16 v[26:29], v[240:243], v[184:187], v[26:29]
	v_mfma_f32_16x16x32_bf16 v[14:17], v[232:235], v[192:195], v[14:17]
	v_mfma_f32_16x16x32_bf16 v[10:13], v[240:243], v[192:195], v[10:13]
	v_mfma_f32_16x16x32_bf16 v[6:9], v[232:235], v[224:227], v[6:9]
	v_mfma_f32_16x16x32_bf16 v[2:5], v[240:243], v[224:227], v[2:5]
	s_add_i32 s39, 0, 0x18000
	s_barrier
	ds_read_b128 v[144:147], v141 offset:32768
	ds_read_b128 v[148:151], v141 offset:33792
	ds_read_b128 v[152:155], v141 offset:34816
	ds_read_b128 v[168:171], v141 offset:35840
	s_add_u32 s50, s50, 0x80000
	s_addc_u32 s51, s51, 0
	s_mov_b32 m0, s56
	ds_read_b128 v[172:175], v143 offset:32768
	ds_read_b128 v[176:179], v143 offset:33792
	ds_read_b128 v[180:183], v143 offset:34816
	ds_read_b128 v[184:187], v143 offset:35840
	ds_read_b128 v[188:191], v143 offset:36864
	ds_read_b128 v[192:195], v143 offset:37888
	ds_read_b128 v[196:199], v143 offset:38912
	ds_read_b128 v[224:227], v143 offset:39936
	global_load_lds_dwordx4 v130, s[50:51]
	s_mov_b32 m0, s57
	s_nop 0
	global_load_lds_dwordx4 v132, s[50:51]
	s_waitcnt lgkmcnt(8)
	s_barrier
	s_waitcnt lgkmcnt(0)
	s_waitcnt lgkmcnt(0)
	v_mfma_f32_16x16x32_bf16 v[126:129], v[144:147], v[172:175], v[126:129]
	v_mfma_f32_16x16x32_bf16 v[122:125], v[152:155], v[172:175], v[122:125]
	v_mfma_f32_16x16x32_bf16 v[118:121], v[144:147], v[180:183], v[118:121]
	v_mfma_f32_16x16x32_bf16 v[114:117], v[152:155], v[180:183], v[114:117]
	v_mfma_f32_16x16x32_bf16 v[102:105], v[144:147], v[188:191], v[102:105]
	v_mfma_f32_16x16x32_bf16 v[98:101], v[152:155], v[188:191], v[98:101]
	v_mfma_f32_16x16x32_bf16 v[86:89], v[144:147], v[196:199], v[86:89]
	v_mfma_f32_16x16x32_bf16 v[82:85], v[152:155], v[196:199], v[82:85]
	v_mfma_f32_16x16x32_bf16 v[126:129], v[148:151], v[176:179], v[126:129]
	v_mfma_f32_16x16x32_bf16 v[122:125], v[168:171], v[176:179], v[122:125]
	v_mfma_f32_16x16x32_bf16 v[118:121], v[148:151], v[184:187], v[118:121]
	v_mfma_f32_16x16x32_bf16 v[114:117], v[168:171], v[184:187], v[114:117]
	v_mfma_f32_16x16x32_bf16 v[102:105], v[148:151], v[192:195], v[102:105]
	v_mfma_f32_16x16x32_bf16 v[98:101], v[168:171], v[192:195], v[98:101]
	v_mfma_f32_16x16x32_bf16 v[86:89], v[148:151], v[224:227], v[86:89]
	v_mfma_f32_16x16x32_bf16 v[82:85], v[168:171], v[224:227], v[82:85]
	s_barrier
	s_add_i32 s50, 0, 0x1c000
	s_add_i32 s39, s39, s53
	s_mov_b32 m0, s39
	ds_read_b128 v[228:231], v141 offset:49152
	ds_read_b128 v[232:235], v141 offset:50176
	ds_read_b128 v[236:239], v141 offset:51200
	ds_read_b128 v[240:243], v141 offset:52224
	global_load_lds_dwordx4 v0, s[76:77]
	s_add_i32 m0, s39, 0x2000
	s_nop 0
	global_load_lds_dwordx4 v134, s[76:77]
	s_barrier
	s_waitcnt lgkmcnt(0)
	s_waitcnt lgkmcnt(0)
	v_mfma_f32_16x16x32_bf16 v[110:113], v[228:231], v[172:175], v[110:113]
	v_mfma_f32_16x16x32_bf16 v[106:109], v[236:239], v[172:175], v[106:109]
	v_mfma_f32_16x16x32_bf16 v[94:97], v[228:231], v[180:183], v[94:97]
	v_mfma_f32_16x16x32_bf16 v[90:93], v[236:239], v[180:183], v[90:93]
	v_mfma_f32_16x16x32_bf16 v[78:81], v[228:231], v[188:191], v[78:81]
	v_mfma_f32_16x16x32_bf16 v[74:77], v[236:239], v[188:191], v[74:77]
	v_mfma_f32_16x16x32_bf16 v[70:73], v[228:231], v[196:199], v[70:73]
	v_mfma_f32_16x16x32_bf16 v[66:69], v[236:239], v[196:199], v[66:69]
	v_mfma_f32_16x16x32_bf16 v[110:113], v[232:235], v[176:179], v[110:113]
	v_mfma_f32_16x16x32_bf16 v[106:109], v[240:243], v[176:179], v[106:109]
	v_mfma_f32_16x16x32_bf16 v[94:97], v[232:235], v[184:187], v[94:97]
	v_mfma_f32_16x16x32_bf16 v[90:93], v[240:243], v[184:187], v[90:93]
	v_mfma_f32_16x16x32_bf16 v[78:81], v[232:235], v[192:195], v[78:81]
	v_mfma_f32_16x16x32_bf16 v[74:77], v[240:243], v[192:195], v[74:77]
	v_mfma_f32_16x16x32_bf16 v[70:73], v[232:235], v[224:227], v[70:73]
	v_mfma_f32_16x16x32_bf16 v[66:69], v[240:243], v[224:227], v[66:69]
	s_mov_b32 m0, s59
	s_barrier
	ds_read_b128 v[172:175], v143 offset:49152
	ds_read_b128 v[176:179], v143 offset:50176
	ds_read_b128 v[180:183], v143 offset:51200
	ds_read_b128 v[184:187], v143 offset:52224
	ds_read_b128 v[188:191], v143 offset:53248
	ds_read_b128 v[192:195], v143 offset:54272
	ds_read_b128 v[196:199], v143 offset:55296
	ds_read_b128 v[224:227], v143 offset:56320
	global_load_lds_dwordx4 v130, s[78:79]
	s_mov_b32 m0, s61
	s_nop 0
	global_load_lds_dwordx4 v132, s[78:79]
	s_barrier
	s_waitcnt lgkmcnt(0)
	s_waitcnt lgkmcnt(0)
	v_mfma_f32_16x16x32_bf16 v[62:65], v[144:147], v[172:175], v[62:65]
	v_mfma_f32_16x16x32_bf16 v[58:61], v[152:155], v[172:175], v[58:61]
	v_mfma_f32_16x16x32_bf16 v[54:57], v[144:147], v[180:183], v[54:57]
	v_mfma_f32_16x16x32_bf16 v[50:53], v[152:155], v[180:183], v[50:53]
	v_mfma_f32_16x16x32_bf16 v[38:41], v[144:147], v[188:191], v[38:41]
	v_mfma_f32_16x16x32_bf16 v[34:37], v[152:155], v[188:191], v[34:37]
	v_mfma_f32_16x16x32_bf16 v[22:25], v[144:147], v[196:199], v[22:25]
	v_mfma_f32_16x16x32_bf16 v[18:21], v[152:155], v[196:199], v[18:21]
	v_mfma_f32_16x16x32_bf16 v[62:65], v[148:151], v[176:179], v[62:65]
	v_mfma_f32_16x16x32_bf16 v[58:61], v[168:171], v[176:179], v[58:61]
	v_mfma_f32_16x16x32_bf16 v[54:57], v[148:151], v[184:187], v[54:57]
	v_mfma_f32_16x16x32_bf16 v[50:53], v[168:171], v[184:187], v[50:53]
	v_mfma_f32_16x16x32_bf16 v[38:41], v[148:151], v[192:195], v[38:41]
	v_mfma_f32_16x16x32_bf16 v[34:37], v[168:171], v[192:195], v[34:37]
	v_mfma_f32_16x16x32_bf16 v[22:25], v[148:151], v[224:227], v[22:25]
	v_mfma_f32_16x16x32_bf16 v[18:21], v[168:171], v[224:227], v[18:21]
	s_barrier
	s_add_u32 s48, s48, 0x80080
	s_addc_u32 s49, s49, 0
	s_add_i32 s39, s50, s53
	s_mov_b32 m0, s39
	s_nop 0
	global_load_lds_dwordx4 v0, s[48:49]
	s_add_i32 m0, s39, 0x2000
	s_nop 0
	global_load_lds_dwordx4 v134, s[48:49]
	s_waitcnt vmcnt(6)
	s_barrier
	v_mfma_f32_16x16x32_bf16 v[46:49], v[228:231], v[172:175], v[46:49]
	v_mfma_f32_16x16x32_bf16 v[42:45], v[236:239], v[172:175], v[42:45]
	v_mfma_f32_16x16x32_bf16 v[30:33], v[228:231], v[180:183], v[30:33]
	v_mfma_f32_16x16x32_bf16 v[26:29], v[236:239], v[180:183], v[26:29]
	v_mfma_f32_16x16x32_bf16 v[14:17], v[228:231], v[188:191], v[14:17]
	v_mfma_f32_16x16x32_bf16 v[10:13], v[236:239], v[188:191], v[10:13]
	v_mfma_f32_16x16x32_bf16 v[6:9], v[228:231], v[196:199], v[6:9]
	v_mfma_f32_16x16x32_bf16 v[2:5], v[236:239], v[196:199], v[2:5]
	v_mfma_f32_16x16x32_bf16 v[46:49], v[232:235], v[176:179], v[46:49]
	v_mfma_f32_16x16x32_bf16 v[42:45], v[240:243], v[176:179], v[42:45]
	v_mfma_f32_16x16x32_bf16 v[30:33], v[232:235], v[184:187], v[30:33]
	v_mfma_f32_16x16x32_bf16 v[26:29], v[240:243], v[184:187], v[26:29]
	v_mfma_f32_16x16x32_bf16 v[14:17], v[232:235], v[192:195], v[14:17]
	v_mfma_f32_16x16x32_bf16 v[10:13], v[240:243], v[192:195], v[10:13]
	v_mfma_f32_16x16x32_bf16 v[6:9], v[232:235], v[224:227], v[6:9]
	v_mfma_f32_16x16x32_bf16 v[2:5], v[240:243], v[224:227], v[2:5]
	s_add_i32 s13, s13, 2
	s_add_u32 s46, s46, 0x100
	s_addc_u32 s47, s47, 0
	s_add_u32 s1, s1, 0x100
	s_addc_u32 s12, s12, 0
	s_cmp_gt_u32 s13, 29
	s_barrier
	s_cbranch_scc0 .LBB0_788
	s_cmp_lg_u32 s62, 0
	s_cbranch_scc0 .LBB0_791
	s_lshl_b32 s1, s60, 8
	s_mov_b64 s[12:13], 0
	s_branch .LBB0_792
